# diff sample items split over 64 WGs (4 wave pairs share the key tiles, LDS merge in fixed order); diff tile rescale check made lane-local (partner exchange only on the rare rescale path); x->bf16 prol
# baseline (speedup 1.0000x reference)
; __device__ __forceinline__ void df_attn_phase(int j, float lambda_init, LAS unsigned char* lds, unsigned* ctr) {
;     ...
;     for (;;) {
;         __syncthreads();
;         if (tid == 0) *s_item = (int)atomicAdd(ctr, 1u);
;         __syncthreads();
;         const int item = *s_item;
;         if (item >= N_ITEMS) break;
;         float mx = -1e30f, ls = 0.f;
;         f32x16 o[4];
; #pragma unroll
;         for (int c = 0; c < 4; ++c)
; #pragma unroll
;             for (int r = 0; r < 16; ++r) o[c][r] = 0.f;
;         bf16x8 qf[4];
;         size_t qrow; int hcol;
;         if (item < N_SAMP) {
;             const int bh = item * 4 + wq, b = bh >> 3, h = bh & 7;
;             qrow = (size_t)MP + b * 32 + (lane & 31); hcol = h * 128;
; #pragma unroll
;             for (int s = 0; s < 4; ++s) qf[s] = *(const bf16x8*)(Qb + qrow * 1024 + hcol + comp * 64 + 16 * s + 8 * hi);
;             GlbProv G;
;             G.ck = P->in[4] + ((size_t)(j * 8 + b) * PAST) * 1024 + hcol; G.cv = P->in[5] + ((size_t)(j * 8 + b) * PAST) * 1024 + hcol;
;             G.nk = P->out + O_DFK_S + ((size_t)(j * 8 + b) * 32) * 1024 + hcol; G.nv = P->out + O_DFV_S + ((size_t)(j * 8 + b) * 32) * 1024 + hcol;
;             for (int t = 0; t <= 32; ++t) { G.tile0 = 64 * t; df_tile<GlbProv, true>(G, comp, qf, 64 * t, PAST + 32, lane, mx, ls, o); }
;         } else {
;             const int n = item - N_SAMP, u2 = 31 - (n >> 6), bh = n & 63, b = bh >> 3, h = bh & 7;
;             const size_t rowb = (size_t)b * SEQ;
;             const int qw = 128 * u2 + 32 * wq, my_top = 2 * u2 + (wq >> 1), ntile = 2 * u2 + 2;
;             qrow = rowb + qw + (lane & 31); hcol = h * 128;
; #pragma unroll
;             for (int s = 0; s < 4; ++s) qf[s] = *(const bf16x8*)(Qb + qrow * 1024 + hcol + comp * 64 + 16 * s + 8 * hi);
;             const int kv0_ = tid >> 4, ch = tid & 15;
;             const int kofs = (ch >> 3) * AT_KCOMP + kv0_ * AT_KPITCH + (ch & 7) * 16, vofs = AT_LDSV + (ch >> 2) * AT_VBLK + kv0_ * 64 + (ch & 3) * 16;
;             const bf16_t* kg = Kb + (rowb + kv0_) * 1024 + hcol + ch * 8; const bf16_t* vg = Vb + (rowb + kv0_) * 1024 + hcol + ch * 8;
;             u32x4 ka0 = *(const u32x4*)kg, ka1 = *(const u32x4*)(kg + 32 * 1024), va0 = *(const u32x4*)vg, va1 = *(const u32x4*)(vg + 32 * 1024);
.LBB0_262:
	s_or_b64 exec, exec, s[6:7]
	v_mov_b32_e32 v0, s88
	s_waitcnt lgkmcnt(0)
	s_barrier
	ds_read_b32 v0, v0
	s_mov_b64 s[6:7], -1
	s_waitcnt lgkmcnt(0)
	v_cmp_lt_i32_e32 vcc, 0x83f, v0
	v_readfirstlane_b32 s29, v0
	s_cbranch_vccnz .LBB0_257
	s_cmp_gt_i32 s29, 63
	v_lshlrev_b32_e32 v146, 1, v160
	s_cbranch_scc0 .LBB0_273
	s_add_i32 s37, s29, 0xffffffc0
	s_lshr_b32 s6, s37, 6
	s_sub_i32 s30, 31, s6
	s_lshl_b32 s6, s37, 9
	s_and_b32 s6, s6, 0x7000
	v_lshl_or_b32 v0, s30, 7, v207
	v_or_b32_e32 v178, s6, v0
	s_lshl_b32 s7, s29, 7
	s_and_b32 s28, s7, 0x380
	v_lshlrev_b32_e32 v0, 11, v178
	v_mov_b32_e32 v1, v147
	v_lshl_add_u64 v[0:1], s[14:15], 0, v[0:1]
	s_lshl_b32 s90, s28, 1
	v_lshl_add_u64 v[0:1], v[0:1], 0, s[90:91]
	v_lshl_add_u64 v[0:1], s[22:23], 1, v[0:1]
	v_lshl_add_u64 v[0:1], v[0:1], 0, v[146:147]
	s_mov_b32 s7, s91
	global_load_dwordx4 v[96:99], v[0:1], off
	global_load_dwordx4 v[100:103], v[0:1], off offset:32
	global_load_dwordx4 v[104:107], v[0:1], off offset:64
	global_load_dwordx4 v[108:111], v[0:1], off offset:96
	v_lshl_add_u64 v[0:1], s[6:7], 0, v[158:159]
	v_lshlrev_b64 v[0:1], 11, v[0:1]
	v_lshl_add_u64 v[2:3], s[16:17], 0, v[0:1]
	v_lshl_add_u64 v[2:3], v[2:3], 0, s[90:91]
	v_mov_b32_e32 v169, v147
	v_lshl_add_u64 v[2:3], v[2:3], 0, v[168:169]
	v_lshl_add_u64 v[0:1], s[18:19], 0, v[0:1]
	v_lshl_add_u64 v[0:1], v[0:1], 0, s[90:91]
	v_add_co_u32_e32 v4, vcc, s96, v2
	v_lshl_add_u64 v[0:1], v[0:1], 0, v[168:169]
	s_nop 0
	v_addc_co_u32_e32 v5, vcc, 0, v3, vcc
	v_add_co_u32_e32 v6, vcc, s96, v0
	global_load_dwordx4 v[112:115], v[2:3], off
	global_load_dwordx4 v[120:123], v[0:1], off
	v_addc_co_u32_e32 v7, vcc, 0, v1, vcc
	global_load_dwordx4 v[116:119], v[4:5], off
	global_load_dwordx4 v[124:127], v[6:7], off
	v_add_co_u32_e32 v4, vcc, s48, v2
	s_lshl_b32 s6, s37, 20
	s_nop 0
	v_addc_co_u32_e32 v5, vcc, 0, v3, vcc
	v_add_co_u32_e32 v2, vcc, s49, v2
	s_and_b32 s7, s29, 7
	s_nop 0
	v_addc_co_u32_e32 v3, vcc, 0, v3, vcc
	global_load_dwordx4 v[128:131], v[4:5], off
	global_load_dwordx4 v[132:135], v[2:3], off
	v_add_co_u32_e32 v2, vcc, s48, v0
	s_and_b32 s6, s6, 0x3800000
	s_nop 0
	v_addc_co_u32_e32 v3, vcc, 0, v1, vcc
	v_add_co_u32_e32 v0, vcc, s49, v0
	s_lshl_b32 s7, s7, 8
	s_nop 0
	v_addc_co_u32_e32 v1, vcc, 0, v1, vcc
	global_load_dwordx4 v[136:139], v[2:3], off
	global_load_dwordx4 v[140:143], v[0:1], off
	v_mov_b32_e32 v14, v147
	v_mov_b32_e32 v15, v147
	s_lshl_b32 s30, s30, 1
	s_or_b32 s90, s6, s7
	v_mov_b32_e32 v0, v147
	v_mov_b32_e32 v1, v147
	v_mov_b32_e32 v2, v147
	v_mov_b32_e32 v3, v147
	v_mov_b32_e32 v4, v147
	v_mov_b32_e32 v5, v147
	v_mov_b32_e32 v6, v147
	v_mov_b32_e32 v7, v147
	v_mov_b32_e32 v8, v147
	v_mov_b32_e32 v9, v147
	v_mov_b32_e32 v10, v147
	v_mov_b32_e32 v11, v147
	v_mov_b32_e32 v12, v147
	v_mov_b32_e32 v13, v147
	v_mov_b64_e32 v[30:31], v[14:15]
	v_mov_b64_e32 v[46:47], v[14:15]
	v_mov_b64_e32 v[62:63], v[14:15]
	v_mov_b32_e32 v179, v147
	s_or_b32 s31, s30, s34
	s_mov_b32 s36, 0
	v_lshl_add_u64 v[180:181], v[166:167], 0, s[90:91]
	v_mov_b32_e32 v169, 0
	v_mov_b32_e32 v173, 0xf149f2ca
	v_mov_b64_e32 v[28:29], v[12:13]
	v_mov_b64_e32 v[26:27], v[10:11]
	v_mov_b64_e32 v[24:25], v[8:9]
	v_mov_b64_e32 v[22:23], v[6:7]
	v_mov_b64_e32 v[20:21], v[4:5]
	v_mov_b64_e32 v[18:19], v[2:3]
	v_mov_b64_e32 v[16:17], v[0:1]
	v_mov_b64_e32 v[44:45], v[12:13]
	v_mov_b64_e32 v[42:43], v[10:11]
	v_mov_b64_e32 v[40:41], v[8:9]
	v_mov_b64_e32 v[38:39], v[6:7]
	v_mov_b64_e32 v[36:37], v[4:5]
	v_mov_b64_e32 v[34:35], v[2:3]
	v_mov_b64_e32 v[32:33], v[0:1]
	v_mov_b64_e32 v[60:61], v[12:13]
	v_mov_b64_e32 v[58:59], v[10:11]
	v_mov_b64_e32 v[56:57], v[8:9]
	v_mov_b64_e32 v[54:55], v[6:7]
	v_mov_b64_e32 v[52:53], v[4:5]
	v_mov_b64_e32 v[50:51], v[2:3]
	v_mov_b64_e32 v[48:49], v[0:1]
	s_branch .LBB0_266

; __device__ __forceinline__ unsigned cvtpk(float lo, float hi) { f32x2_t v = {lo, hi}; bf16x2_t b = __builtin_convertvector(v, bf16x2_t); return __builtin_bit_cast(unsigned, b); }
; #define MFMA32(a, b, c) __builtin_amdgcn_mfma_f32_32x32x16_bf16((a), (b), (c), 0, 0, 0)
; template <class Prov, bool MASK>
; __device__ __forceinline__ void df_tile(const Prov& P, int comp, const bf16x8 (&qf)[4], int kv0, int kvlim, int lane, float& mx, float& ls, f32x16 (&o)[4]) {
;     ...
;     float m = fmaxf(s[0][0], s[1][0]);
; #pragma unroll
;     for (int r = 1; r < 16; ++r) m = fmaxf(m, fmaxf(s[0][r], s[1][r]));
;     m = fmaxf(m, __shfl_xor(m, 32));
;     const float mn = fmaxf(mx, m), al = __builtin_amdgcn_exp2f(mx - mn);
;     mx = mn;
;     float ps = 0.f;
; #pragma unroll
;     for (int b2 = 0; b2 < 2; ++b2)
; #pragma unroll
;         for (int r = 0; r < 16; ++r) { const float p = __builtin_amdgcn_exp2f(s[b2][r] - mn); s[b2][r] = p; ps += p; }
;     ls = ls * al + ps;
; #pragma unroll
;     for (int c = 0; c < 4; ++c) o[c] = o[c] * al;
; #pragma unroll
;     for (int kb = 0; kb < 4; ++kb) {
;         const int b2 = kb >> 1, r0 = 8 * (kb & 1);
;         u32x4 w; w.x = cvtpk(s[b2][r0], s[b2][r0 + 1]); w.y = cvtpk(s[b2][r0 + 2], s[b2][r0 + 3]); w.z = cvtpk(s[b2][r0 + 4], s[b2][r0 + 5]); w.w = cvtpk(s[b2][r0 + 6], s[b2][r0 + 7]);
;         const bf16x8 pf = __builtin_bit_cast(bf16x8, w);
; #pragma unroll
;         for (int c = 0; c < 4; ++c) o[c] = MFMA32(P.vfrag(kb, c, lane), pf, o[c]);
;     }
.LBB0_270:
	ds_read_b128 v[64:67], v216 offset:0
	ds_read_b128 v[68:71], v216 offset:32
	ds_read_b128 v[72:75], v216 offset:64
	ds_read_b128 v[76:79], v216 offset:96
	ds_read_b128 v[218:221], v217 offset:0
	ds_read_b128 v[222:225], v217 offset:32
	s_waitcnt lgkmcnt(5)
	v_mfma_f32_32x32x16_bf16 v[80:95], v[64:67], v[96:99], 0
	s_waitcnt lgkmcnt(4)
	v_mfma_f32_32x32x16_bf16 v[80:95], v[68:71], v[100:103], v[80:95]
	s_waitcnt lgkmcnt(3)
	v_mfma_f32_32x32x16_bf16 v[80:95], v[72:75], v[104:107], v[80:95]
	s_waitcnt lgkmcnt(2)
	v_mfma_f32_32x32x16_bf16 v[80:95], v[76:79], v[108:111], v[80:95]
	s_waitcnt lgkmcnt(1)
	v_mfma_f32_32x32x16_bf16 v[64:79], v[218:221], v[96:99], 0
	ds_read_b128 v[218:221], v217 offset:64
	s_waitcnt lgkmcnt(1)
	v_mfma_f32_32x32x16_bf16 v[64:79], v[222:225], v[100:103], v[64:79]
	ds_read_b128 v[222:225], v217 offset:96
	s_waitcnt lgkmcnt(1)
	v_mfma_f32_32x32x16_bf16 v[64:79], v[218:221], v[104:107], v[64:79]
	s_waitcnt lgkmcnt(0)
	v_mfma_f32_32x32x16_bf16 v[64:79], v[222:225], v[108:111], v[64:79]
	ds_read_b64_tr_b16 v[218:219], v200 offset:18432
	ds_read_b64_tr_b16 v[220:221], v200 offset:18944
	ds_read_b64_tr_b16 v[222:223], v200 offset:22528
	ds_read_b64_tr_b16 v[224:225], v200 offset:23040
	v_max3_f32 v171, v80, v81, v82
	v_max3_f32 v175, v83, v84, v85
	v_max3_f32 v171, v171, v86, v87
	v_max3_f32 v175, v175, v88, v89
	v_max3_f32 v171, v171, v90, v91
	v_max3_f32 v175, v175, v92, v93
	v_max3_f32 v171, v171, v94, v95
	s_nop 0
	v_max3_f32 v175, v175, v64, v65
	v_max3_f32 v171, v171, v66, v67
	v_max3_f32 v175, v175, v68, v69
	v_max3_f32 v171, v171, v70, v71
	v_max3_f32 v175, v175, v72, v73
	v_max3_f32 v171, v171, v74, v75
	v_max3_f32 v175, v175, v76, v77
	v_max3_f32 v171, v171, v78, v79
	v_max_f32_e32 v171, v171, v175
	v_sub_f32_e32 v175, v171, v173
	v_cmp_lt_f32_e32 vcc, 0x41000000, v175
	s_and_b64 vcc, exec, vcc
	s_cbranch_vccnz .Ldf0_rs
.Ldf0_go:
	v_sub_f32_e32 v80, v80, v173
	v_sub_f32_e32 v81, v81, v173
	v_sub_f32_e32 v82, v82, v173
	v_sub_f32_e32 v83, v83, v173
	v_sub_f32_e32 v84, v84, v173
	v_sub_f32_e32 v85, v85, v173
	v_sub_f32_e32 v86, v86, v173
	v_sub_f32_e32 v87, v87, v173
	v_exp_f32_e32 v80, v80
	v_exp_f32_e32 v81, v81
	v_exp_f32_e32 v82, v82
	v_exp_f32_e32 v83, v83
	v_exp_f32_e32 v84, v84
	v_exp_f32_e32 v85, v85
	v_exp_f32_e32 v86, v86
	v_exp_f32_e32 v87, v87
	v_sub_f32_e32 v88, v88, v173
	v_sub_f32_e32 v89, v89, v173
	v_sub_f32_e32 v90, v90, v173
	v_sub_f32_e32 v91, v91, v173
	v_sub_f32_e32 v92, v92, v173
	v_sub_f32_e32 v93, v93, v173
	v_sub_f32_e32 v94, v94, v173
	v_sub_f32_e32 v95, v95, v173
	v_exp_f32_e32 v88, v88
	v_exp_f32_e32 v89, v89
	v_exp_f32_e32 v90, v90
	v_exp_f32_e32 v91, v91
	v_exp_f32_e32 v92, v92
	v_exp_f32_e32 v93, v93
	v_exp_f32_e32 v94, v94
	v_exp_f32_e32 v95, v95
	v_add_f32_e32 v169, v169, v80
	v_add_f32_e32 v169, v169, v81
	v_add_f32_e32 v169, v169, v82
	v_add_f32_e32 v169, v169, v83
	v_add_f32_e32 v169, v169, v84
	v_add_f32_e32 v169, v169, v85
	v_add_f32_e32 v169, v169, v86
	v_add_f32_e32 v169, v169, v87
	v_sub_f32_e32 v64, v64, v173
	v_sub_f32_e32 v65, v65, v173
	v_sub_f32_e32 v66, v66, v173
	v_sub_f32_e32 v67, v67, v173
	v_sub_f32_e32 v68, v68, v173
	v_sub_f32_e32 v69, v69, v173
	v_sub_f32_e32 v70, v70, v173
	v_sub_f32_e32 v71, v71, v173
	v_exp_f32_e32 v64, v64
	v_exp_f32_e32 v65, v65
	v_exp_f32_e32 v66, v66
	v_exp_f32_e32 v67, v67
	v_exp_f32_e32 v68, v68
	v_exp_f32_e32 v69, v69
	v_exp_f32_e32 v70, v70
	v_exp_f32_e32 v71, v71
	v_add_f32_e32 v169, v169, v88
	v_add_f32_e32 v169, v169, v89
	v_add_f32_e32 v169, v169, v90
	v_add_f32_e32 v169, v169, v91
	v_add_f32_e32 v169, v169, v92
	v_add_f32_e32 v169, v169, v93
	v_add_f32_e32 v169, v169, v94
	v_add_f32_e32 v169, v169, v95
	v_sub_f32_e32 v72, v72, v173
	v_sub_f32_e32 v73, v73, v173
	v_sub_f32_e32 v74, v74, v173
	v_sub_f32_e32 v75, v75, v173
	v_sub_f32_e32 v76, v76, v173
	v_sub_f32_e32 v77, v77, v173
	v_sub_f32_e32 v78, v78, v173
	v_sub_f32_e32 v79, v79, v173
	v_exp_f32_e32 v72, v72
	v_exp_f32_e32 v73, v73
	v_exp_f32_e32 v74, v74
	v_exp_f32_e32 v75, v75
	v_exp_f32_e32 v76, v76
	v_exp_f32_e32 v77, v77
	v_exp_f32_e32 v78, v78
	v_exp_f32_e32 v79, v79
	v_add_f32_e32 v169, v169, v64
	v_add_f32_e32 v169, v169, v65
	v_add_f32_e32 v169, v169, v66
	v_add_f32_e32 v169, v169, v67
	v_add_f32_e32 v169, v169, v68
	v_add_f32_e32 v169, v169, v69
	v_add_f32_e32 v169, v169, v70
	v_add_f32_e32 v169, v169, v71
	v_add_f32_e32 v169, v169, v72
	v_add_f32_e32 v169, v169, v73
	v_add_f32_e32 v169, v169, v74
	v_add_f32_e32 v169, v169, v75
	v_add_f32_e32 v169, v169, v76
	v_add_f32_e32 v169, v169, v77
	v_add_f32_e32 v169, v169, v78
	v_add_f32_e32 v169, v169, v79
	v_cvt_pk_bf16_f32 v80, v80, v81
	v_cvt_pk_bf16_f32 v81, v82, v83
	v_cvt_pk_bf16_f32 v82, v84, v85
	v_cvt_pk_bf16_f32 v83, v86, v87
	v_cvt_pk_bf16_f32 v88, v88, v89
	v_cvt_pk_bf16_f32 v89, v90, v91
	v_cvt_pk_bf16_f32 v90, v92, v93
	v_cvt_pk_bf16_f32 v91, v94, v95
	v_cvt_pk_bf16_f32 v64, v64, v65
	v_cvt_pk_bf16_f32 v65, v66, v67
	v_cvt_pk_bf16_f32 v66, v68, v69
	v_cvt_pk_bf16_f32 v67, v70, v71
	v_cvt_pk_bf16_f32 v72, v72, v73
	v_cvt_pk_bf16_f32 v73, v74, v75
	v_cvt_pk_bf16_f32 v74, v76, v77
	v_cvt_pk_bf16_f32 v75, v78, v79
	ds_read_b64_tr_b16 v[84:85], v200 offset:26624
	ds_read_b64_tr_b16 v[86:87], v200 offset:27136
	ds_read_b64_tr_b16 v[92:93], v200 offset:30720
	ds_read_b64_tr_b16 v[94:95], v200 offset:31232
	ds_read_b64_tr_b16 v[68:69], v200 offset:19456
	ds_read_b64_tr_b16 v[70:71], v200 offset:19968
	ds_read_b64_tr_b16 v[76:77], v200 offset:23552
	ds_read_b64_tr_b16 v[78:79], v200 offset:24064
	s_waitcnt lgkmcnt(10)
; __device__ __forceinline__ unsigned cvtpk(float lo, float hi) { f32x2_t v = {lo, hi}; bf16x2_t b = __builtin_convertvector(v, bf16x2_t); return __builtin_bit_cast(unsigned, b); }
; #define MFMA32(a, b, c) __builtin_amdgcn_mfma_f32_32x32x16_bf16((a), (b), (c), 0, 0, 0)
; template <class Prov, bool MASK>
; __device__ __forceinline__ void df_tile(const Prov& P, int comp, const bf16x8 (&qf)[4], int kv0, int kvlim, int lane, float& mx, float& ls, f32x16 (&o)[4]) {
;     ...
;     for (int ss = 0; ss < 4; ++ss) { s[0] = MFMA32(P.kfrag(comp, 0, ss, lane), qf[ss], s[0]); s[1] = MFMA32(P.kfrag(comp, 1, ss, lane), qf[ss], s[1]); }
;     if (MASK) {
; #pragma unroll
;         for (int b2 = 0; b2 < 2; ++b2)
; #pragma unroll
;             for (int r = 0; r < 16; ++r) { const int kvp = kv0 + 32 * b2 + (r & 3) + 8 * (r >> 2) + 4 * hi; if (kvp >= kvlim) s[b2][r] = -1e30f; }
;     }
;     float m = fmaxf(s[0][0], s[1][0]);
; #pragma unroll
;     for (int r = 1; r < 16; ++r) m = fmaxf(m, fmaxf(s[0][r], s[1][r]));
;     m = fmaxf(m, __shfl_xor(m, 32));
;     const float mn = fmaxf(mx, m), al = __builtin_amdgcn_exp2f(mx - mn);
;     ...
;     for (int kb = 0; kb < 4; ++kb) {
;         const int b2 = kb >> 1, r0 = 8 * (kb & 1);
;         u32x4 w; w.x = cvtpk(s[b2][r0], s[b2][r0 + 1]); w.y = cvtpk(s[b2][r0 + 2], s[b2][r0 + 3]); w.z = cvtpk(s[b2][r0 + 4], s[b2][r0 + 5]); w.w = cvtpk(s[b2][r0 + 6], s[b2][r0 + 7]);
;         const bf16x8 pf = __builtin_bit_cast(bf16x8, w);
; #pragma unroll
;         for (int c = 0; c < 4; ++c) o[c] = MFMA32(P.vfrag(kb, c, lane), pf, o[c]);
;     }
	v_mfma_f32_32x32x16_bf16 v[48:63], v[218:221], v[80:83], v[48:63]
	ds_read_b64_tr_b16 v[218:219], v200 offset:27648
	ds_read_b64_tr_b16 v[220:221], v200 offset:28160
	s_waitcnt lgkmcnt(10)
	v_mfma_f32_32x32x16_bf16 v[32:47], v[222:225], v[80:83], v[32:47]
	ds_read_b64_tr_b16 v[222:223], v200 offset:31744
	ds_read_b64_tr_b16 v[224:225], v200 offset:32256
	s_waitcnt lgkmcnt(10)
	v_mfma_f32_32x32x16_bf16 v[16:31], v[84:87], v[80:83], v[16:31]
	ds_read_b64_tr_b16 v[84:85], v200 offset:20480
	ds_read_b64_tr_b16 v[86:87], v200 offset:20992
	s_waitcnt lgkmcnt(10)
	v_mfma_f32_32x32x16_bf16 v[0:15], v[92:95], v[80:83], v[0:15]
	ds_read_b64_tr_b16 v[92:93], v200 offset:24576
	ds_read_b64_tr_b16 v[94:95], v200 offset:25088
	s_waitcnt lgkmcnt(10)
	v_mfma_f32_32x32x16_bf16 v[48:63], v[68:71], v[88:91], v[48:63]
	ds_read_b64_tr_b16 v[68:69], v200 offset:28672
	ds_read_b64_tr_b16 v[70:71], v200 offset:29184
	s_waitcnt lgkmcnt(10)
	v_mfma_f32_32x32x16_bf16 v[32:47], v[76:79], v[88:91], v[32:47]
	ds_read_b64_tr_b16 v[76:77], v200 offset:32768
	ds_read_b64_tr_b16 v[78:79], v200 offset:33280
	s_waitcnt lgkmcnt(10)
	v_mfma_f32_32x32x16_bf16 v[16:31], v[218:221], v[88:91], v[16:31]
	ds_read_b64_tr_b16 v[218:219], v200 offset:21504
	ds_read_b64_tr_b16 v[220:221], v200 offset:22016
	s_waitcnt lgkmcnt(10)
	v_mfma_f32_32x32x16_bf16 v[0:15], v[222:225], v[88:91], v[0:15]
	ds_read_b64_tr_b16 v[222:223], v200 offset:25600
	ds_read_b64_tr_b16 v[224:225], v200 offset:26112
	s_waitcnt lgkmcnt(10)
	v_mfma_f32_32x32x16_bf16 v[48:63], v[84:87], v[64:67], v[48:63]
	ds_read_b64_tr_b16 v[84:85], v200 offset:29696
	ds_read_b64_tr_b16 v[86:87], v200 offset:30208
	s_waitcnt lgkmcnt(10)
	v_mfma_f32_32x32x16_bf16 v[32:47], v[92:95], v[64:67], v[32:47]
	ds_read_b64_tr_b16 v[92:93], v200 offset:33792
	ds_read_b64_tr_b16 v[94:95], v200 offset:34304
	s_waitcnt lgkmcnt(10)
	v_mfma_f32_32x32x16_bf16 v[16:31], v[68:71], v[64:67], v[16:31]
	s_waitcnt lgkmcnt(8)
	v_mfma_f32_32x32x16_bf16 v[0:15], v[76:79], v[64:67], v[0:15]
	s_waitcnt lgkmcnt(6)
	v_mfma_f32_32x32x16_bf16 v[48:63], v[218:221], v[72:75], v[48:63]
	s_waitcnt lgkmcnt(4)
	v_mfma_f32_32x32x16_bf16 v[32:47], v[222:225], v[72:75], v[32:47]
	s_waitcnt lgkmcnt(2)
	v_mfma_f32_32x32x16_bf16 v[16:31], v[84:87], v[72:75], v[16:31]
	s_waitcnt lgkmcnt(0)
	v_mfma_f32_32x32x16_bf16 v[0:15], v[92:95], v[72:75], v[0:15]
	s_cmp_ge_u32 s36, s31
	s_cbranch_scc1 .LBB0_265
.LBB0_271:
	ds_read_b128 v[64:67], v216 offset:34816
	ds_read_b128 v[68:71], v216 offset:34848
	ds_read_b128 v[72:75], v216 offset:34880
	ds_read_b128 v[76:79], v216 offset:34912
	ds_read_b128 v[218:221], v217 offset:34816
	ds_read_b128 v[222:225], v217 offset:34848
	s_waitcnt lgkmcnt(5)
	v_mfma_f32_32x32x16_bf16 v[80:95], v[64:67], v[96:99], 0
	s_waitcnt lgkmcnt(4)
	v_mfma_f32_32x32x16_bf16 v[80:95], v[68:71], v[100:103], v[80:95]
	s_waitcnt lgkmcnt(3)
	v_mfma_f32_32x32x16_bf16 v[80:95], v[72:75], v[104:107], v[80:95]
	s_waitcnt lgkmcnt(2)
	v_mfma_f32_32x32x16_bf16 v[80:95], v[76:79], v[108:111], v[80:95]
	s_waitcnt lgkmcnt(1)
	v_mfma_f32_32x32x16_bf16 v[64:79], v[218:221], v[96:99], 0
	ds_read_b128 v[218:221], v217 offset:34880
	s_waitcnt lgkmcnt(1)
	v_mfma_f32_32x32x16_bf16 v[64:79], v[222:225], v[100:103], v[64:79]
	ds_read_b128 v[222:225], v217 offset:34912
	s_waitcnt lgkmcnt(1)
	v_mfma_f32_32x32x16_bf16 v[64:79], v[218:221], v[104:107], v[64:79]
	s_waitcnt lgkmcnt(0)
	v_mfma_f32_32x32x16_bf16 v[64:79], v[222:225], v[108:111], v[64:79]
	ds_read_b64_tr_b16 v[218:219], v201 offset:0
	ds_read_b64_tr_b16 v[220:221], v201 offset:512
	ds_read_b64_tr_b16 v[222:223], v201 offset:4096
	ds_read_b64_tr_b16 v[224:225], v201 offset:4608
	v_max3_f32 v171, v80, v81, v82
	v_max3_f32 v175, v83, v84, v85
	v_max3_f32 v171, v171, v86, v87
	v_max3_f32 v175, v175, v88, v89
	v_max3_f32 v171, v171, v90, v91
	v_max3_f32 v175, v175, v92, v93
	v_max3_f32 v171, v171, v94, v95
	s_nop 0
	v_max3_f32 v175, v175, v64, v65
	v_max3_f32 v171, v171, v66, v67
	v_max3_f32 v175, v175, v68, v69
	v_max3_f32 v171, v171, v70, v71
	v_max3_f32 v175, v175, v72, v73
	v_max3_f32 v171, v171, v74, v75
	v_max3_f32 v175, v175, v76, v77
	v_max3_f32 v171, v171, v78, v79
	v_max_f32_e32 v171, v171, v175
	v_sub_f32_e32 v175, v171, v173
	v_cmp_lt_f32_e32 vcc, 0x41000000, v175
	s_and_b64 vcc, exec, vcc
	s_cbranch_vccnz .Ldf1_rs
; __device__ __forceinline__ unsigned cvtpk(float lo, float hi) { f32x2_t v = {lo, hi}; bf16x2_t b = __builtin_convertvector(v, bf16x2_t); return __builtin_bit_cast(unsigned, b); }
; #define MFMA32(a, b, c) __builtin_amdgcn_mfma_f32_32x32x16_bf16((a), (b), (c), 0, 0, 0)
; template <class Prov, bool MASK>
; __device__ __forceinline__ void df_tile(const Prov& P, int comp, const bf16x8 (&qf)[4], int kv0, int kvlim, int lane, float& mx, float& ls, f32x16 (&o)[4]) {
;     ...
;     const float mn = fmaxf(mx, m), al = __builtin_amdgcn_exp2f(mx - mn);
;     mx = mn;
;     float ps = 0.f;
; #pragma unroll
;     for (int b2 = 0; b2 < 2; ++b2)
; #pragma unroll
;         for (int r = 0; r < 16; ++r) { const float p = __builtin_amdgcn_exp2f(s[b2][r] - mn); s[b2][r] = p; ps += p; }
;     ls = ls * al + ps;
; #pragma unroll
;     for (int c = 0; c < 4; ++c) o[c] = o[c] * al;
; #pragma unroll
;     for (int kb = 0; kb < 4; ++kb) {
;         const int b2 = kb >> 1, r0 = 8 * (kb & 1);
;         u32x4 w; w.x = cvtpk(s[b2][r0], s[b2][r0 + 1]); w.y = cvtpk(s[b2][r0 + 2], s[b2][r0 + 3]); w.z = cvtpk(s[b2][r0 + 4], s[b2][r0 + 5]); w.w = cvtpk(s[b2][r0 + 6], s[b2][r0 + 7]);
;         const bf16x8 pf = __builtin_bit_cast(bf16x8, w);
; #pragma unroll
;         for (int c = 0; c < 4; ++c) o[c] = MFMA32(P.vfrag(kb, c, lane), pf, o[c]);
;     }
.Ldf1_go:
	v_sub_f32_e32 v80, v80, v173
	v_sub_f32_e32 v81, v81, v173
	v_sub_f32_e32 v82, v82, v173
	v_sub_f32_e32 v83, v83, v173
	v_sub_f32_e32 v84, v84, v173
	v_sub_f32_e32 v85, v85, v173
	v_sub_f32_e32 v86, v86, v173
	v_sub_f32_e32 v87, v87, v173
	v_exp_f32_e32 v80, v80
	v_exp_f32_e32 v81, v81
	v_exp_f32_e32 v82, v82
	v_exp_f32_e32 v83, v83
	v_exp_f32_e32 v84, v84
	v_exp_f32_e32 v85, v85
	v_exp_f32_e32 v86, v86
	v_exp_f32_e32 v87, v87
	v_sub_f32_e32 v88, v88, v173
	v_sub_f32_e32 v89, v89, v173
	v_sub_f32_e32 v90, v90, v173
	v_sub_f32_e32 v91, v91, v173
	v_sub_f32_e32 v92, v92, v173
	v_sub_f32_e32 v93, v93, v173
	v_sub_f32_e32 v94, v94, v173
	v_sub_f32_e32 v95, v95, v173
	v_exp_f32_e32 v88, v88
	v_exp_f32_e32 v89, v89
	v_exp_f32_e32 v90, v90
	v_exp_f32_e32 v91, v91
	v_exp_f32_e32 v92, v92
	v_exp_f32_e32 v93, v93
	v_exp_f32_e32 v94, v94
	v_exp_f32_e32 v95, v95
	v_add_f32_e32 v169, v169, v80
	v_add_f32_e32 v169, v169, v81
	v_add_f32_e32 v169, v169, v82
	v_add_f32_e32 v169, v169, v83
	v_add_f32_e32 v169, v169, v84
	v_add_f32_e32 v169, v169, v85
	v_add_f32_e32 v169, v169, v86
	v_add_f32_e32 v169, v169, v87
	v_sub_f32_e32 v64, v64, v173
	v_sub_f32_e32 v65, v65, v173
	v_sub_f32_e32 v66, v66, v173
	v_sub_f32_e32 v67, v67, v173
	v_sub_f32_e32 v68, v68, v173
	v_sub_f32_e32 v69, v69, v173
	v_sub_f32_e32 v70, v70, v173
	v_sub_f32_e32 v71, v71, v173
	v_exp_f32_e32 v64, v64
	v_exp_f32_e32 v65, v65
	v_exp_f32_e32 v66, v66
	v_exp_f32_e32 v67, v67
	v_exp_f32_e32 v68, v68
	v_exp_f32_e32 v69, v69
	v_exp_f32_e32 v70, v70
	v_exp_f32_e32 v71, v71
	v_add_f32_e32 v169, v169, v88
	v_add_f32_e32 v169, v169, v89
	v_add_f32_e32 v169, v169, v90
	v_add_f32_e32 v169, v169, v91
	v_add_f32_e32 v169, v169, v92
	v_add_f32_e32 v169, v169, v93
	v_add_f32_e32 v169, v169, v94
	v_add_f32_e32 v169, v169, v95
	v_sub_f32_e32 v72, v72, v173
	v_sub_f32_e32 v73, v73, v173
	v_sub_f32_e32 v74, v74, v173
	v_sub_f32_e32 v75, v75, v173
	v_sub_f32_e32 v76, v76, v173
	v_sub_f32_e32 v77, v77, v173
	v_sub_f32_e32 v78, v78, v173
	v_sub_f32_e32 v79, v79, v173
	v_exp_f32_e32 v72, v72
	v_exp_f32_e32 v73, v73
	v_exp_f32_e32 v74, v74
	v_exp_f32_e32 v75, v75
	v_exp_f32_e32 v76, v76
	v_exp_f32_e32 v77, v77
	v_exp_f32_e32 v78, v78
	v_exp_f32_e32 v79, v79
	v_add_f32_e32 v169, v169, v64
	v_add_f32_e32 v169, v169, v65
	v_add_f32_e32 v169, v169, v66
	v_add_f32_e32 v169, v169, v67
	v_add_f32_e32 v169, v169, v68
	v_add_f32_e32 v169, v169, v69
	v_add_f32_e32 v169, v169, v70
	v_add_f32_e32 v169, v169, v71
	v_add_f32_e32 v169, v169, v72
	v_add_f32_e32 v169, v169, v73
	v_add_f32_e32 v169, v169, v74
	v_add_f32_e32 v169, v169, v75
	v_add_f32_e32 v169, v169, v76
	v_add_f32_e32 v169, v169, v77
	v_add_f32_e32 v169, v169, v78
	v_add_f32_e32 v169, v169, v79
	v_cvt_pk_bf16_f32 v80, v80, v81
	v_cvt_pk_bf16_f32 v81, v82, v83
	v_cvt_pk_bf16_f32 v82, v84, v85
	v_cvt_pk_bf16_f32 v83, v86, v87
	v_cvt_pk_bf16_f32 v88, v88, v89
	v_cvt_pk_bf16_f32 v89, v90, v91
	v_cvt_pk_bf16_f32 v90, v92, v93
	v_cvt_pk_bf16_f32 v91, v94, v95
	v_cvt_pk_bf16_f32 v64, v64, v65
	v_cvt_pk_bf16_f32 v65, v66, v67
	v_cvt_pk_bf16_f32 v66, v68, v69
	v_cvt_pk_bf16_f32 v67, v70, v71
	v_cvt_pk_bf16_f32 v72, v72, v73
	v_cvt_pk_bf16_f32 v73, v74, v75
	v_cvt_pk_bf16_f32 v74, v76, v77
	v_cvt_pk_bf16_f32 v75, v78, v79
	ds_read_b64_tr_b16 v[84:85], v201 offset:8192
	ds_read_b64_tr_b16 v[86:87], v201 offset:8704
	ds_read_b64_tr_b16 v[92:93], v201 offset:12288
	ds_read_b64_tr_b16 v[94:95], v201 offset:12800
	ds_read_b64_tr_b16 v[68:69], v201 offset:1024
	ds_read_b64_tr_b16 v[70:71], v201 offset:1536
	ds_read_b64_tr_b16 v[76:77], v201 offset:5120
	ds_read_b64_tr_b16 v[78:79], v201 offset:5632
	s_waitcnt lgkmcnt(10)
	v_mfma_f32_32x32x16_bf16 v[48:63], v[218:221], v[80:83], v[48:63]
	ds_read_b64_tr_b16 v[218:219], v201 offset:9216
	ds_read_b64_tr_b16 v[220:221], v201 offset:9728
	s_waitcnt lgkmcnt(10)
	v_mfma_f32_32x32x16_bf16 v[32:47], v[222:225], v[80:83], v[32:47]
	ds_read_b64_tr_b16 v[222:223], v201 offset:13312
	ds_read_b64_tr_b16 v[224:225], v201 offset:13824
	s_waitcnt lgkmcnt(10)
	v_mfma_f32_32x32x16_bf16 v[16:31], v[84:87], v[80:83], v[16:31]
	ds_read_b64_tr_b16 v[84:85], v201 offset:2048
	ds_read_b64_tr_b16 v[86:87], v201 offset:2560
	s_waitcnt lgkmcnt(10)
	v_mfma_f32_32x32x16_bf16 v[0:15], v[92:95], v[80:83], v[0:15]
	ds_read_b64_tr_b16 v[92:93], v201 offset:6144
	ds_read_b64_tr_b16 v[94:95], v201 offset:6656
	s_waitcnt lgkmcnt(10)
	v_mfma_f32_32x32x16_bf16 v[48:63], v[68:71], v[88:91], v[48:63]
	ds_read_b64_tr_b16 v[68:69], v201 offset:10240
	ds_read_b64_tr_b16 v[70:71], v201 offset:10752
	s_waitcnt lgkmcnt(10)
	v_mfma_f32_32x32x16_bf16 v[32:47], v[76:79], v[88:91], v[32:47]
	ds_read_b64_tr_b16 v[76:77], v201 offset:14336
	ds_read_b64_tr_b16 v[78:79], v201 offset:14848
	s_waitcnt lgkmcnt(10)
	v_mfma_f32_32x32x16_bf16 v[16:31], v[218:221], v[88:91], v[16:31]
	ds_read_b64_tr_b16 v[218:219], v201 offset:3072
	ds_read_b64_tr_b16 v[220:221], v201 offset:3584
	s_waitcnt lgkmcnt(10)
	v_mfma_f32_32x32x16_bf16 v[0:15], v[222:225], v[88:91], v[0:15]
	ds_read_b64_tr_b16 v[222:223], v201 offset:7168
	ds_read_b64_tr_b16 v[224:225], v201 offset:7680
	s_waitcnt lgkmcnt(10)
	v_mfma_f32_32x32x16_bf16 v[48:63], v[84:87], v[64:67], v[48:63]
	ds_read_b64_tr_b16 v[84:85], v201 offset:11264
	ds_read_b64_tr_b16 v[86:87], v201 offset:11776
	s_waitcnt lgkmcnt(10)
	v_mfma_f32_32x32x16_bf16 v[32:47], v[92:95], v[64:67], v[32:47]
	ds_read_b64_tr_b16 v[92:93], v201 offset:15360
	ds_read_b64_tr_b16 v[94:95], v201 offset:15872
	s_waitcnt lgkmcnt(10)
	v_mfma_f32_32x32x16_bf16 v[16:31], v[68:71], v[64:67], v[16:31]
	s_waitcnt lgkmcnt(8)
	v_mfma_f32_32x32x16_bf16 v[0:15], v[76:79], v[64:67], v[0:15]
	s_waitcnt lgkmcnt(6)
	v_mfma_f32_32x32x16_bf16 v[48:63], v[218:221], v[72:75], v[48:63]
	s_waitcnt lgkmcnt(4)
	v_mfma_f32_32x32x16_bf16 v[32:47], v[222:225], v[72:75], v[32:47]
	s_waitcnt lgkmcnt(2)
	v_mfma_f32_32x32x16_bf16 v[16:31], v[84:87], v[72:75], v[16:31]
	s_waitcnt lgkmcnt(0)
	v_mfma_f32_32x32x16_bf16 v[0:15], v[92:95], v[72:75], v[0:15]
	s_branch .LBB0_265
; template <class Prov, bool MASK>
; __device__ __forceinline__ void df_tile(const Prov& P, int comp, const bf16x8 (&qf)[4], int kv0, int kvlim, int lane, float& mx, float& ls, f32x16 (&o)[4]) {
;     ...
;     m = fmaxf(m, __shfl_xor(m, 32));
;     const float mn = fmaxf(mx, m), al = __builtin_amdgcn_exp2f(mx - mn);
;     mx = mn;
;     float ps = 0.f;
; #pragma unroll
;     for (int b2 = 0; b2 < 2; ++b2)
; #pragma unroll
;         for (int r = 0; r < 16; ++r) { const float p = __builtin_amdgcn_exp2f(s[b2][r] - mn); s[b2][r] = p; ps += p; }
;     ls = ls * al + ps;
; #pragma unroll
;     for (int c = 0; c < 4; ++c) o[c] = o[c] * al;
.Ldf0_rs:
	ds_bpermute_b32 v175, v161, v171
	s_waitcnt lgkmcnt(0)
	v_max3_f32 v171, v171, v175, v173
	v_sub_f32_e32 v175, v173, v171
	v_exp_f32_e32 v175, v175
	v_mov_b32_e32 v173, v171
	v_mul_f32_e32 v169, v169, v175
	v_mul_f32_e32 v0, v0, v175
	v_mul_f32_e32 v1, v1, v175
	v_mul_f32_e32 v2, v2, v175
	v_mul_f32_e32 v3, v3, v175
	v_mul_f32_e32 v4, v4, v175
	v_mul_f32_e32 v5, v5, v175
	v_mul_f32_e32 v6, v6, v175
	v_mul_f32_e32 v7, v7, v175
	v_mul_f32_e32 v8, v8, v175
	v_mul_f32_e32 v9, v9, v175
	v_mul_f32_e32 v10, v10, v175
	v_mul_f32_e32 v11, v11, v175
	v_mul_f32_e32 v12, v12, v175
	v_mul_f32_e32 v13, v13, v175
	v_mul_f32_e32 v14, v14, v175
	v_mul_f32_e32 v15, v15, v175
	v_mul_f32_e32 v16, v16, v175
	v_mul_f32_e32 v17, v17, v175
	v_mul_f32_e32 v18, v18, v175
	v_mul_f32_e32 v19, v19, v175
	v_mul_f32_e32 v20, v20, v175
	v_mul_f32_e32 v21, v21, v175
	v_mul_f32_e32 v22, v22, v175
	v_mul_f32_e32 v23, v23, v175
	v_mul_f32_e32 v24, v24, v175
	v_mul_f32_e32 v25, v25, v175
	v_mul_f32_e32 v26, v26, v175
	v_mul_f32_e32 v27, v27, v175
	v_mul_f32_e32 v28, v28, v175
	v_mul_f32_e32 v29, v29, v175
	v_mul_f32_e32 v30, v30, v175
	v_mul_f32_e32 v31, v31, v175
	v_mul_f32_e32 v32, v32, v175
	v_mul_f32_e32 v33, v33, v175
	v_mul_f32_e32 v34, v34, v175
	v_mul_f32_e32 v35, v35, v175
	v_mul_f32_e32 v36, v36, v175
	v_mul_f32_e32 v37, v37, v175
	v_mul_f32_e32 v38, v38, v175
	v_mul_f32_e32 v39, v39, v175
	v_mul_f32_e32 v40, v40, v175
	v_mul_f32_e32 v41, v41, v175
	v_mul_f32_e32 v42, v42, v175
	v_mul_f32_e32 v43, v43, v175
	v_mul_f32_e32 v44, v44, v175
	v_mul_f32_e32 v45, v45, v175
	v_mul_f32_e32 v46, v46, v175
	v_mul_f32_e32 v47, v47, v175
	v_mul_f32_e32 v48, v48, v175
	v_mul_f32_e32 v49, v49, v175
	v_mul_f32_e32 v50, v50, v175
	v_mul_f32_e32 v51, v51, v175
	v_mul_f32_e32 v52, v52, v175
	v_mul_f32_e32 v53, v53, v175
	v_mul_f32_e32 v54, v54, v175
	v_mul_f32_e32 v55, v55, v175
	v_mul_f32_e32 v56, v56, v175
	v_mul_f32_e32 v57, v57, v175
	v_mul_f32_e32 v58, v58, v175
	v_mul_f32_e32 v59, v59, v175
	v_mul_f32_e32 v60, v60, v175
	v_mul_f32_e32 v61, v61, v175
	v_mul_f32_e32 v62, v62, v175
	v_mul_f32_e32 v63, v63, v175
	s_branch .Ldf0_go

; __device__ __forceinline__ unsigned cvtpk(float lo, float hi) { f32x2_t v = {lo, hi}; bf16x2_t b = __builtin_convertvector(v, bf16x2_t); return __builtin_bit_cast(unsigned, b); }
;     __device__ __forceinline__ bf16x8 kfrag(int comp, int b2, int s, int lane) const {
;         const float* p = rowp(ck, nk, tile0 + 32 * b2 + (lane & 31)) + comp * 64 + 16 * s + 8 * (lane >> 5);
;         const f32x4 a = *(const f32x4*)p, b = *(const f32x4*)(p + 4);
;         u32x4 w; w.x = cvtpk(a[0], a[1]); w.y = cvtpk(a[2], a[3]); w.z = cvtpk(b[0], b[1]); w.w = cvtpk(b[2], b[3]);
;         return __builtin_bit_cast(bf16x8, w);
; __device__ __forceinline__ void df_attn_phase(int j, float lambda_init, LAS unsigned char* lds, unsigned* ctr) {
;     ...
;             const int bh = item * 4 + wq, b = bh >> 3, h = bh & 7;
;             qrow = (size_t)MP + b * 32 + (lane & 31); hcol = h * 128;
; #pragma unroll
;             for (int s = 0; s < 4; ++s) qf[s] = *(const bf16x8*)(Qb + qrow * 1024 + hcol + comp * 64 + 16 * s + 8 * hi);
;             GlbProv G;
;             G.ck = P->in[4] + ((size_t)(j * 8 + b) * PAST) * 1024 + hcol; G.cv = P->in[5] + ((size_t)(j * 8 + b) * PAST) * 1024 + hcol;
;             G.nk = P->out + O_DFK_S + ((size_t)(j * 8 + b) * 32) * 1024 + hcol; G.nv = P->out + O_DFV_S + ((size_t)(j * 8 + b) * 32) * 1024 + hcol;
;             for (int t = 0; t <= 32; ++t) { G.tile0 = 64 * t; df_tile<GlbProv, true>(G, comp, qf, 64 * t, PAST + 32, lane, mx, ls, o); }
.LBB0_273:
	s_and_b64 vcc, exec, s[6:7]
	s_cbranch_vccz .LBB0_276
	s_and_b32 s30, s29, 7
	s_ashr_i32 s29, s29, 3
	s_lshl_b32 s6, s29, 5
	s_ashr_i32 s7, s6, 31
	v_lshl_add_u64 v[178:179], s[6:7], 0, v[162:163]
	v_lshlrev_b64 v[0:1], 11, v[178:179]
	v_lshl_add_u64 v[0:1], s[14:15], 0, v[0:1]
	s_lshl_b32 s90, s30, 8
	v_lshl_add_u64 v[0:1], v[0:1], 0, s[90:91]
	v_lshl_add_u64 v[0:1], s[22:23], 1, v[0:1]
	v_lshl_add_u64 v[0:1], v[0:1], 0, v[146:147]
	global_load_dwordx4 v[96:99], v[0:1], off
	global_load_dwordx4 v[100:103], v[0:1], off offset:32
	global_load_dwordx4 v[104:107], v[0:1], off offset:64
	global_load_dwordx4 v[108:111], v[0:1], off offset:96
	s_load_dwordx4 s[36:39], s[0:1], 0x20
	s_add_i32 s6, s29, s35
	s_ashr_i32 s7, s6, 31
	s_lshl_b32 s28, s30, 7
	s_lshl_b64 s[40:41], s[6:7], 23
	s_waitcnt lgkmcnt(0)
	s_add_u32 s29, s36, s40
	s_addc_u32 s30, s37, s41
	s_add_u32 s31, s38, s40
	s_addc_u32 s36, s39, s41
	s_load_dwordx2 s[38:39], s[0:1], 0xa8
	s_lshl_b64 s[6:7], s[6:7], 17
	v_mov_b32_e32 v169, 0
	s_waitcnt vmcnt(11)
	v_mov_b32_e32 v113, 0xf149f2ca
	s_lshl_b32 s41, s13, 18
	s_waitcnt lgkmcnt(0)
	s_add_u32 s6, s38, s6
	s_addc_u32 s7, s39, s7
	s_add_u32 s37, s6, 0x48500000
	s_addc_u32 s38, s7, 0
	s_add_u32 s39, s6, 0x48700000
	s_addc_u32 s40, s7, 0
	s_lshl_b32 s42, s28, 2
	s_lshl_b32 s43, s13, 6
	v_mov_b32_e32 v48, 0
	v_mov_b32_e32 v49, v169
	v_mov_b32_e32 v50, v169
	v_mov_b32_e32 v51, v169
	v_mov_b32_e32 v52, v169
	v_mov_b32_e32 v53, v169
	v_mov_b32_e32 v54, v169
	v_mov_b32_e32 v55, v169
	v_mov_b32_e32 v56, v169
	v_mov_b32_e32 v57, v169
	v_mov_b32_e32 v58, v169
	v_mov_b32_e32 v59, v169
	v_mov_b32_e32 v60, v169
	v_mov_b32_e32 v61, v169
	v_mov_b32_e32 v62, v169
	v_mov_b32_e32 v63, v169
	v_mov_b32_e32 v32, 0
	v_mov_b32_e32 v33, v169
	v_mov_b32_e32 v34, v169
	v_mov_b32_e32 v35, v169
	v_mov_b32_e32 v36, v169
	v_mov_b32_e32 v37, v169
	v_mov_b32_e32 v38, v169
	v_mov_b32_e32 v39, v169
	v_mov_b32_e32 v40, v169
	v_mov_b32_e32 v41, v169
	v_mov_b32_e32 v42, v169
	v_mov_b32_e32 v43, v169
	v_mov_b32_e32 v44, v169
	v_mov_b32_e32 v45, v169
	v_mov_b32_e32 v46, v169
	v_mov_b32_e32 v47, v169
	v_mov_b32_e32 v16, 0
	v_mov_b32_e32 v17, v169
	v_mov_b32_e32 v18, v169
	v_mov_b32_e32 v19, v169
	v_mov_b32_e32 v20, v169
	v_mov_b32_e32 v21, v169
	v_mov_b32_e32 v22, v169
	v_mov_b32_e32 v23, v169
	v_mov_b32_e32 v24, v169
	v_mov_b32_e32 v25, v169
	v_mov_b32_e32 v26, v169
	v_mov_b32_e32 v27, v169
	v_mov_b32_e32 v28, v169
	v_mov_b32_e32 v29, v169
	v_mov_b32_e32 v30, v169
	v_mov_b32_e32 v31, v169
	v_mov_b32_e32 v0, 0
	v_mov_b32_e32 v1, v169
	v_mov_b32_e32 v2, v169
	v_mov_b32_e32 v3, v169
	v_mov_b32_e32 v4, v169
	v_mov_b32_e32 v5, v169
	v_mov_b32_e32 v6, v169
	v_mov_b32_e32 v7, v169
	v_mov_b32_e32 v8, v169
	v_mov_b32_e32 v9, v169
	v_mov_b32_e32 v10, v169
	v_mov_b32_e32 v11, v169
	v_mov_b32_e32 v12, v169
	v_mov_b32_e32 v13, v169
	v_mov_b32_e32 v14, v169
	v_mov_b32_e32 v15, v169
.LBB0_275:
	s_cmpk_eq_i32 s43, 0x800
	s_cselect_b64 vcc, -1, 0
	v_add_u32_e32 v64, s43, v156
	s_and_b64 s[6:7], vcc, exec
	v_add_u32_e32 v65, 0xfffff800, v64
	s_cselect_b32 s6, s37, s29
	v_cndmask_b32_e32 v146, v64, v65, vcc
	s_cselect_b32 s7, s38, s30
	s_cselect_b32 s44, s40, s36
	s_cselect_b32 s45, s39, s31
	s_add_u32 s6, s6, s42
	s_addc_u32 s7, s7, 0
	v_lshlrev_b64 v[64:65], 12, v[146:147]
	v_lshl_add_u64 v[64:65], s[6:7], 0, v[64:65]
	s_lshl_b64 s[46:47], s[22:23], 2
	v_lshl_add_u64 v[64:65], v[64:65], 0, s[46:47]
	v_mov_b32_e32 v171, v147
	s_waitcnt vmcnt(9)
	v_lshl_add_u64 v[122:123], v[64:65], 0, v[170:171]
	v_add_u32_e32 v64, s41, v213
	v_cndmask_b32_e32 v146, v64, v194, vcc
	v_lshl_add_u64 v[64:65], s[6:7], 0, v[146:147]
	v_lshl_add_u64 v[64:65], v[64:65], 0, s[46:47]
	s_waitcnt vmcnt(8)
	v_lshl_add_u64 v[124:125], v[64:65], 0, v[170:171]
	global_load_dwordx4 v[64:67], v[122:123], off offset:16
	global_load_dwordx4 v[68:71], v[122:123], off
	global_load_dwordx4 v[80:83], v[124:125], off offset:16
	global_load_dwordx4 v[84:87], v[124:125], off
	global_load_dwordx4 v[114:117], v[122:123], off offset:80
	global_load_dwordx4 v[118:121], v[122:123], off offset:64
	v_add_u32_e32 v112, s43, v206
	s_movk_i32 s6, 0x7ff
	v_cmp_gt_u32_e64 s[6:7], s6, v112
	s_waitcnt vmcnt(13)
	v_mov_b32_e32 v130, v169
	s_waitcnt vmcnt(4)
	v_cvt_pk_bf16_f32 v68, v68, v69
	v_cvt_pk_bf16_f32 v69, v70, v71
	v_cvt_pk_bf16_f32 v70, v64, v65
	v_cvt_pk_bf16_f32 v71, v66, v67
	s_waitcnt vmcnt(0)
	v_cvt_pk_bf16_f32 v118, v118, v119
	v_cvt_pk_bf16_f32 v119, v120, v121
	v_mfma_f32_32x32x16_bf16 v[64:79], v[68:71], v[96:99], 0
	v_cvt_pk_bf16_f32 v120, v114, v115
	v_cvt_pk_bf16_f32 v121, v116, v117
	v_cvt_pk_bf16_f32 v84, v84, v85
	v_cvt_pk_bf16_f32 v85, v86, v87
	v_cvt_pk_bf16_f32 v86, v80, v81
	v_cvt_pk_bf16_f32 v87, v82, v83
	v_mfma_f32_32x32x16_bf16 v[64:79], v[118:121], v[100:103], v[64:79]
	global_load_dwordx4 v[114:117], v[124:125], off offset:80
	global_load_dwordx4 v[118:121], v[124:125], off offset:64
	s_waitcnt vmcnt(0)
	v_cvt_pk_bf16_f32 v118, v118, v119
	v_mfma_f32_32x32x16_bf16 v[80:95], v[84:87], v[96:99], 0
	v_cvt_pk_bf16_f32 v119, v120, v121
	v_cvt_pk_bf16_f32 v120, v114, v115
	v_cvt_pk_bf16_f32 v121, v116, v117
	s_nop 1
	v_mfma_f32_32x32x16_bf16 v[80:95], v[118:121], v[100:103], v[80:95]
	global_load_dwordx4 v[114:117], v[122:123], off offset:144
	global_load_dwordx4 v[118:121], v[122:123], off offset:128
	s_waitcnt vmcnt(0)
	v_cvt_pk_bf16_f32 v118, v118, v119
	v_cvt_pk_bf16_f32 v119, v120, v121
	v_cvt_pk_bf16_f32 v120, v114, v115
	v_cvt_pk_bf16_f32 v121, v116, v117
	s_nop 1
	v_mfma_f32_32x32x16_bf16 v[64:79], v[118:121], v[104:107], v[64:79]
	global_load_dwordx4 v[114:117], v[124:125], off offset:144
	global_load_dwordx4 v[118:121], v[124:125], off offset:128
	s_waitcnt vmcnt(0)
; #define MFMA32(a, b, c) __builtin_amdgcn_mfma_f32_32x32x16_bf16((a), (b), (c), 0, 0, 0)
; template <class Prov, bool MASK>
; __device__ __forceinline__ void df_tile(const Prov& P, int comp, const bf16x8 (&qf)[4], int kv0, int kvlim, int lane, float& mx, float& ls, f32x16 (&o)[4]) {
;     ...
;     for (int ss = 0; ss < 4; ++ss) { s[0] = MFMA32(P.kfrag(comp, 0, ss, lane), qf[ss], s[0]); s[1] = MFMA32(P.kfrag(comp, 1, ss, lane), qf[ss], s[1]); }
;     if (MASK) {
; #pragma unroll
;         for (int b2 = 0; b2 < 2; ++b2)
; #pragma unroll
;             for (int r = 0; r < 16; ++r) { const int kvp = kv0 + 32 * b2 + (r & 3) + 8 * (r >> 2) + 4 * hi; if (kvp >= kvlim) s[b2][r] = -1e30f; }
;     }
;     float m = fmaxf(s[0][0], s[1][0]);
; #pragma unroll
;     for (int r = 1; r < 16; ++r) m = fmaxf(m, fmaxf(s[0][r], s[1][r]));
;     m = fmaxf(m, __shfl_xor(m, 32));
;     const float mn = fmaxf(mx, m), al = __builtin_amdgcn_exp2f(mx - mn);
;     mx = mn;
;     float ps = 0.f;
; #pragma unroll
;     for (int b2 = 0; b2 < 2; ++b2)
; #pragma unroll
;         for (int r = 0; r < 16; ++r) { const float p = __builtin_amdgcn_exp2f(s[b2][r] - mn); s[b2][r] = p; ps += p; }
	v_cvt_pk_bf16_f32 v118, v118, v119
	v_cvt_pk_bf16_f32 v119, v120, v121
	v_cvt_pk_bf16_f32 v120, v114, v115
	v_cvt_pk_bf16_f32 v121, v116, v117
	s_nop 1
	v_mfma_f32_32x32x16_bf16 v[80:95], v[118:121], v[104:107], v[80:95]
	global_load_dwordx4 v[114:117], v[122:123], off offset:208
	global_load_dwordx4 v[118:121], v[122:123], off offset:192
	s_waitcnt vmcnt(0)
	v_cvt_pk_bf16_f32 v118, v118, v119
	v_cvt_pk_bf16_f32 v119, v120, v121
	v_cvt_pk_bf16_f32 v120, v114, v115
	v_cvt_pk_bf16_f32 v121, v116, v117
	s_nop 1
	v_mfma_f32_32x32x16_bf16 v[64:79], v[118:121], v[108:111], v[64:79]
	global_load_dwordx4 v[114:117], v[124:125], off offset:208
	global_load_dwordx4 v[118:121], v[124:125], off offset:192
	s_waitcnt vmcnt(0)
	v_cvt_pk_bf16_f32 v118, v118, v119
	v_cvt_pk_bf16_f32 v119, v120, v121
	v_cvt_pk_bf16_f32 v120, v114, v115
	v_cvt_pk_bf16_f32 v121, v116, v117
	s_nop 1
	v_mfma_f32_32x32x16_bf16 v[80:95], v[118:121], v[108:111], v[80:95]
	s_nop 11
	v_cndmask_b32_e64 v81, v195, v81, s[6:7]
	s_movk_i32 s6, 0x7fe
	v_cmp_gt_u32_e64 s[6:7], s6, v112
	v_cndmask_b32_e32 v117, v88, v195, vcc
	v_max_f32_e32 v88, v81, v81
	v_cndmask_b32_e64 v82, v195, v82, s[6:7]
	s_movk_i32 s6, 0x7fd
	v_cmp_gt_u32_e64 s[6:7], s6, v112
	v_cndmask_b32_e32 v80, v80, v195, vcc
	v_cndmask_b32_e32 v84, v84, v195, vcc
	v_cndmask_b32_e64 v83, v195, v83, s[6:7]
	s_movk_i32 s6, 0x7f7
	v_cmp_gt_u32_e64 s[6:7], s6, v112
	v_cndmask_b32_e32 v121, v92, v195, vcc
	s_nop 0
	v_cndmask_b32_e64 v85, v195, v85, s[6:7]
	s_movk_i32 s6, 0x7f6
	v_cmp_gt_u32_e64 s[6:7], s6, v112
	s_nop 1
	v_cndmask_b32_e64 v86, v195, v86, s[6:7]
	s_movk_i32 s6, 0x7f5
	v_cmp_gt_u32_e64 s[6:7], s6, v112
	s_nop 1
	v_cndmask_b32_e64 v87, v195, v87, s[6:7]
	s_movk_i32 s6, 0x7ef
	v_cmp_gt_u32_e64 s[6:7], s6, v112
	s_nop 1
	v_cndmask_b32_e64 v118, v195, v89, s[6:7]
	s_movk_i32 s6, 0x7ee
	v_cmp_gt_u32_e64 s[6:7], s6, v112
	v_max_f32_e32 v89, v65, v65
	v_max_f32_e32 v88, v89, v88
	v_cndmask_b32_e64 v119, v195, v90, s[6:7]
	s_movk_i32 s6, 0x7ed
	v_cmp_gt_u32_e64 s[6:7], s6, v112
	v_max_f32_e32 v89, v82, v82
	v_max_f32_e32 v90, v66, v66
	v_cndmask_b32_e64 v120, v195, v91, s[6:7]
	v_max_f32_e32 v89, v90, v89
	v_max_f32_e32 v90, v83, v83
	v_max_f32_e32 v91, v67, v67
	v_max3_f32 v88, v64, v80, v88
	v_max_f32_e32 v90, v91, v90
	v_max3_f32 v88, v88, v89, v90
	v_max_f32_e32 v89, v84, v84
	v_max_f32_e32 v90, v68, v68
	v_max_f32_e32 v89, v90, v89
	v_max_f32_e32 v90, v85, v85
	v_max_f32_e32 v91, v69, v69
	v_max_f32_e32 v90, v91, v90
	v_max3_f32 v88, v88, v89, v90
	v_max_f32_e32 v89, v86, v86
	v_max_f32_e32 v90, v70, v70
	v_max_f32_e32 v89, v90, v89
	v_max_f32_e32 v90, v87, v87
	v_max_f32_e32 v91, v71, v71
	v_max_f32_e32 v90, v91, v90
	v_max3_f32 v88, v88, v89, v90
	v_max_f32_e32 v89, v117, v117
	v_max_f32_e32 v90, v72, v72
	v_max_f32_e32 v89, v90, v89
	v_max_f32_e32 v90, v118, v118
	v_max_f32_e32 v91, v73, v73
	v_max_f32_e32 v90, v91, v90
	s_movk_i32 s6, 0x7e7
	v_max3_f32 v88, v88, v89, v90
	v_max_f32_e32 v89, v119, v119
	v_max_f32_e32 v90, v74, v74
	v_cmp_gt_u32_e64 s[6:7], s6, v112
	v_max_f32_e32 v89, v90, v89
	v_max_f32_e32 v90, v120, v120
	v_max_f32_e32 v91, v75, v75
	v_cndmask_b32_e64 v122, v195, v93, s[6:7]
	s_movk_i32 s6, 0x7e6
	v_max_f32_e32 v90, v91, v90
	v_cmp_gt_u32_e64 s[6:7], s6, v112
	v_max3_f32 v88, v88, v89, v90
	v_max_f32_e32 v89, v121, v121
	v_max_f32_e32 v90, v76, v76
	v_cndmask_b32_e64 v123, v195, v94, s[6:7]
	s_movk_i32 s6, 0x7e5
	v_max_f32_e32 v89, v90, v89
	v_max_f32_e32 v90, v122, v122
	v_max_f32_e32 v91, v77, v77
	v_cmp_gt_u32_e64 s[6:7], s6, v112
	v_max_f32_e32 v90, v91, v90
	v_max3_f32 v88, v88, v89, v90
	v_cndmask_b32_e64 v124, v195, v95, s[6:7]
	v_max_f32_e32 v89, v123, v123
	v_max_f32_e32 v90, v78, v78
	v_max_f32_e32 v89, v90, v89
	v_max_f32_e32 v90, v124, v124
	v_max_f32_e32 v91, v79, v79
	v_max_f32_e32 v90, v91, v90
	v_max3_f32 v88, v88, v89, v90
	ds_bpermute_b32 v89, v161, v88
	s_add_u32 s6, s45, s42
	s_addc_u32 s7, s44, 0
	s_waitcnt lgkmcnt(0)
	v_max3_f32 v116, v113, v88, v89
	v_sub_f32_e32 v64, v64, v116
	v_exp_f32_e32 v132, v64
	v_sub_f32_e32 v65, v65, v116
	v_exp_f32_e32 v65, v65
	v_sub_f32_e32 v66, v66, v116
	v_exp_f32_e32 v66, v66
	v_sub_f32_e32 v67, v67, v116
	v_exp_f32_e32 v67, v67
	v_sub_f32_e32 v68, v68, v116
	v_add_f32_e32 v64, 0, v132
	v_exp_f32_e32 v68, v68
	v_sub_f32_e32 v69, v69, v116
	v_add_f32_e32 v64, v65, v64
	v_exp_f32_e32 v69, v69
	v_sub_f32_e32 v70, v70, v116
	v_add_f32_e32 v64, v66, v64
	v_exp_f32_e32 v70, v70
	v_sub_f32_e32 v71, v71, v116
	v_add_f32_e32 v64, v67, v64
	v_exp_f32_e32 v71, v71
	v_sub_f32_e32 v72, v72, v116
	v_sub_f32_e32 v131, v113, v116
	v_add_f32_e32 v64, v68, v64
	v_exp_f32_e32 v113, v72
	v_sub_f32_e32 v72, v73, v116
	v_add_f32_e32 v64, v69, v64
	v_exp_f32_e32 v114, v72
	v_sub_f32_e32 v72, v74, v116
	v_add_f32_e32 v64, v70, v64
	v_exp_f32_e32 v115, v72
	v_sub_f32_e32 v72, v75, v116
	v_add_f32_e32 v64, v71, v64
	v_exp_f32_e32 v125, v72
	v_sub_f32_e32 v72, v76, v116
	v_add_f32_e32 v64, v113, v64
	v_exp_f32_e32 v126, v72
	v_sub_f32_e32 v72, v77, v116
	v_add_f32_e32 v64, v114, v64
	v_exp_f32_e32 v127, v72
	v_sub_f32_e32 v72, v78, v116
	v_add_f32_e32 v64, v115, v64
	v_exp_f32_e32 v128, v72
	v_sub_f32_e32 v72, v79, v116
	v_add_f32_e32 v64, v125, v64
	v_exp_f32_e32 v129, v72
	v_sub_f32_e32 v72, v80, v116
	v_add_f32_e32 v64, v126, v64
	v_exp_f32_e32 v88, v72
	v_sub_f32_e32 v72, v81, v116
	v_add_f32_e32 v64, v127, v64
	v_exp_f32_e32 v89, v72
	v_sub_f32_e32 v72, v82, v116
	v_add_f32_e32 v64, v128, v64
	v_exp_f32_e32 v90, v72
	v_sub_f32_e32 v72, v83, v116
	v_add_f32_e32 v64, v129, v64
	v_exp_f32_e32 v91, v72
	v_sub_f32_e32 v72, v84, v116
	v_add_f32_e32 v64, v88, v64
; __device__ __forceinline__ unsigned cvtpk(float lo, float hi) { f32x2_t v = {lo, hi}; bf16x2_t b = __builtin_convertvector(v, bf16x2_t); return __builtin_bit_cast(unsigned, b); }
; #define MFMA32(a, b, c) __builtin_amdgcn_mfma_f32_32x32x16_bf16((a), (b), (c), 0, 0, 0)
;     __device__ __forceinline__ bf16x8 vfrag(int kb, int c, int lane) const {
;         const int h = lane >> 5, dcol = 32 * c + (lane & 31);
;         float v[8];
; #pragma unroll
;         for (int i = 0; i < 8; ++i) v[i] = rowp(cv, nv, tile0 + 16 * kb + (i & 3) + 8 * (i >> 2) + 4 * h)[dcol];
;         u32x4 w; w.x = cvtpk(v[0], v[1]); w.y = cvtpk(v[2], v[3]); w.z = cvtpk(v[4], v[5]); w.w = cvtpk(v[6], v[7]);
;         return __builtin_bit_cast(bf16x8, w);
; template <class Prov, bool MASK>
; __device__ __forceinline__ void df_tile(const Prov& P, int comp, const bf16x8 (&qf)[4], int kv0, int kvlim, int lane, float& mx, float& ls, f32x16 (&o)[4]) {
;     ...
;         for (int r = 0; r < 16; ++r) { const float p = __builtin_amdgcn_exp2f(s[b2][r] - mn); s[b2][r] = p; ps += p; }
;     ls = ls * al + ps;
; #pragma unroll
;     for (int c = 0; c < 4; ++c) o[c] = o[c] * al;
; #pragma unroll
;     for (int kb = 0; kb < 4; ++kb) {
;         const int b2 = kb >> 1, r0 = 8 * (kb & 1);
;         u32x4 w; w.x = cvtpk(s[b2][r0], s[b2][r0 + 1]); w.y = cvtpk(s[b2][r0 + 2], s[b2][r0 + 3]); w.z = cvtpk(s[b2][r0 + 4], s[b2][r0 + 5]); w.w = cvtpk(s[b2][r0 + 6], s[b2][r0 + 7]);
;         const bf16x8 pf = __builtin_bit_cast(bf16x8, w);
; #pragma unroll
;         for (int c = 0; c < 4; ++c) o[c] = MFMA32(P.vfrag(kb, c, lane), pf, o[c]);
	v_exp_f32_e32 v92, v72
	v_sub_f32_e32 v72, v85, v116
	v_add_f32_e32 v64, v89, v64
	v_exp_f32_e32 v93, v72
	v_sub_f32_e32 v72, v86, v116
	v_add_f32_e32 v64, v90, v64
	v_exp_f32_e32 v94, v72
	v_sub_f32_e32 v72, v87, v116
	v_add_f32_e32 v64, v91, v64
	v_exp_f32_e32 v95, v72
	v_sub_f32_e32 v72, v117, v116
	v_add_f32_e32 v64, v92, v64
	v_exp_f32_e32 v117, v72
	v_sub_f32_e32 v72, v118, v116
	v_add_f32_e32 v64, v93, v64
	v_exp_f32_e32 v118, v72
	v_sub_f32_e32 v72, v119, v116
	v_add_f32_e32 v64, v94, v64
	v_exp_f32_e32 v119, v72
	v_sub_f32_e32 v72, v120, v116
	v_add_f32_e32 v64, v95, v64
	v_exp_f32_e32 v120, v72
	v_sub_f32_e32 v72, v121, v116
	v_add_f32_e32 v64, v117, v64
	v_exp_f32_e32 v121, v72
	v_sub_f32_e32 v72, v122, v116
	v_add_f32_e32 v64, v118, v64
	v_exp_f32_e32 v122, v72
	v_sub_f32_e32 v72, v123, v116
	v_add_f32_e32 v64, v119, v64
	v_exp_f32_e32 v123, v72
	v_sub_f32_e32 v72, v124, v116
	v_add_f32_e32 v64, v120, v64
	v_exp_f32_e32 v124, v72
	v_add_f32_e32 v64, v121, v64
	v_add_f32_e32 v64, v122, v64
	v_add_f32_e32 v64, v123, v64
	v_add_f32_e32 v169, v124, v64
	v_exp_f32_e32 v64, v131
	v_add_u32_e32 v131, s43, v205
	v_or_b32_e32 v76, 3, v131
	v_add_u32_e32 v72, 1, v112
	v_fmac_f32_e32 v169, v130, v64
	v_pk_mul_f32 v[62:63], v[62:63], v[64:65] op_sel_hi:[1,0]
	v_pk_mul_f32 v[60:61], v[60:61], v[64:65] op_sel_hi:[1,0]
	v_pk_mul_f32 v[58:59], v[58:59], v[64:65] op_sel_hi:[1,0]
	v_pk_mul_f32 v[56:57], v[56:57], v[64:65] op_sel_hi:[1,0]
	v_pk_mul_f32 v[54:55], v[54:55], v[64:65] op_sel_hi:[1,0]
	v_pk_mul_f32 v[52:53], v[52:53], v[64:65] op_sel_hi:[1,0]
	v_pk_mul_f32 v[50:51], v[50:51], v[64:65] op_sel_hi:[1,0]
	v_pk_mul_f32 v[48:49], v[48:49], v[64:65] op_sel_hi:[1,0]
	v_pk_mul_f32 v[46:47], v[46:47], v[64:65] op_sel_hi:[1,0]
	v_pk_mul_f32 v[44:45], v[44:45], v[64:65] op_sel_hi:[1,0]
	v_pk_mul_f32 v[42:43], v[42:43], v[64:65] op_sel_hi:[1,0]
	v_pk_mul_f32 v[40:41], v[40:41], v[64:65] op_sel_hi:[1,0]
	v_pk_mul_f32 v[38:39], v[38:39], v[64:65] op_sel_hi:[1,0]
	v_pk_mul_f32 v[36:37], v[36:37], v[64:65] op_sel_hi:[1,0]
	v_pk_mul_f32 v[34:35], v[34:35], v[64:65] op_sel_hi:[1,0]
	v_pk_mul_f32 v[32:33], v[32:33], v[64:65] op_sel_hi:[1,0]
	v_pk_mul_f32 v[30:31], v[30:31], v[64:65] op_sel_hi:[1,0]
	v_pk_mul_f32 v[28:29], v[28:29], v[64:65] op_sel_hi:[1,0]
	v_pk_mul_f32 v[26:27], v[26:27], v[64:65] op_sel_hi:[1,0]
	v_pk_mul_f32 v[24:25], v[24:25], v[64:65] op_sel_hi:[1,0]
	v_pk_mul_f32 v[22:23], v[22:23], v[64:65] op_sel_hi:[1,0]
	v_pk_mul_f32 v[20:21], v[20:21], v[64:65] op_sel_hi:[1,0]
	v_pk_mul_f32 v[18:19], v[18:19], v[64:65] op_sel_hi:[1,0]
	v_pk_mul_f32 v[16:17], v[16:17], v[64:65] op_sel_hi:[1,0]
	v_pk_mul_f32 v[14:15], v[14:15], v[64:65] op_sel_hi:[1,0]
	v_pk_mul_f32 v[12:13], v[12:13], v[64:65] op_sel_hi:[1,0]
	v_pk_mul_f32 v[10:11], v[10:11], v[64:65] op_sel_hi:[1,0]
	v_pk_mul_f32 v[8:9], v[8:9], v[64:65] op_sel_hi:[1,0]
	v_pk_mul_f32 v[6:7], v[6:7], v[64:65] op_sel_hi:[1,0]
	v_pk_mul_f32 v[4:5], v[4:5], v[64:65] op_sel_hi:[1,0]
	v_pk_mul_f32 v[2:3], v[2:3], v[64:65] op_sel_hi:[1,0]
	v_pk_mul_f32 v[0:1], v[0:1], v[64:65] op_sel_hi:[1,0]
	v_cvt_pk_bf16_f32 v64, v132, v65
	v_or_b32_e32 v132, 11, v131
	v_cvt_pk_bf16_f32 v65, v66, v67
	v_cvt_pk_bf16_f32 v66, v68, v69
	v_add_u32_e32 v68, 0xfffff800, v112
	v_add_u32_e32 v73, 0xfffff801, v112
	v_add_u32_e32 v74, 2, v112
	v_add_u32_e32 v75, 0xfffff802, v112
	v_add_u32_e32 v77, 0xfffff800, v76
	v_add_u32_e32 v78, 8, v112
	v_add_u32_e32 v79, 0xfffff808, v112
	v_add_u32_e32 v80, 9, v112
	v_add_u32_e32 v81, 0xfffff809, v112
	v_add_u32_e32 v84, 10, v112
	v_add_u32_e32 v85, 0xfffff80a, v112
	v_add_u32_e32 v133, 0xfffff800, v132
	v_cndmask_b32_e32 v146, v112, v68, vcc
	v_cndmask_b32_e32 v72, v72, v73, vcc
	v_mov_b32_e32 v73, v147
	v_cndmask_b32_e32 v74, v74, v75, vcc
	v_mov_b32_e32 v75, v147
	v_cndmask_b32_e32 v76, v76, v77, vcc
	v_mov_b32_e32 v77, v147
	v_cndmask_b32_e32 v78, v78, v79, vcc
	v_mov_b32_e32 v79, v147
	v_cndmask_b32_e32 v80, v80, v81, vcc
	v_mov_b32_e32 v81, v147
	v_cndmask_b32_e32 v84, v84, v85, vcc
	v_mov_b32_e32 v85, v147
	v_cndmask_b32_e32 v132, v132, v133, vcc
	v_mov_b32_e32 v133, v147
	v_lshlrev_b64 v[68:69], 12, v[146:147]
	v_lshlrev_b64 v[72:73], 12, v[72:73]
	v_lshlrev_b64 v[74:75], 12, v[74:75]
	v_lshlrev_b64 v[76:77], 12, v[76:77]
	v_lshlrev_b64 v[78:79], 12, v[78:79]
	v_lshlrev_b64 v[80:81], 12, v[80:81]
	v_lshlrev_b64 v[84:85], 12, v[84:85]
	v_lshlrev_b64 v[132:133], 12, v[132:133]
	v_lshl_add_u64 v[68:69], s[6:7], 0, v[68:69]
	v_lshlrev_b32_e32 v146, 2, v156
	v_lshl_add_u64 v[72:73], s[6:7], 0, v[72:73]
	v_lshl_add_u64 v[74:75], s[6:7], 0, v[74:75]
	v_lshl_add_u64 v[76:77], s[6:7], 0, v[76:77]
	v_lshl_add_u64 v[78:79], s[6:7], 0, v[78:79]
	v_lshl_add_u64 v[80:81], s[6:7], 0, v[80:81]
	v_lshl_add_u64 v[84:85], s[6:7], 0, v[84:85]
	v_lshl_add_u64 v[180:181], s[6:7], 0, v[132:133]
	v_cvt_pk_bf16_f32 v67, v70, v71
	v_lshl_add_u64 v[70:71], v[68:69], 0, v[146:147]
	v_lshl_add_u64 v[82:83], v[72:73], 0, v[146:147]
	v_lshl_add_u64 v[86:87], v[74:75], 0, v[146:147]
	v_lshl_add_u64 v[136:137], v[76:77], 0, v[146:147]
	v_lshl_add_u64 v[138:139], v[78:79], 0, v[146:147]
	v_lshl_add_u64 v[140:141], v[80:81], 0, v[146:147]
	v_lshl_add_u64 v[142:143], v[84:85], 0, v[146:147]
	v_lshl_add_u64 v[218:219], v[180:181], 0, v[146:147]
	global_load_dword v130, v[70:71], off
	global_load_dword v134, v[82:83], off
	global_load_dword v135, v[86:87], off
	global_load_dword v171, v[136:137], off
	global_load_dword v173, v[138:139], off
	global_load_dword v175, v[140:141], off
	global_load_dword v177, v[142:143], off
	global_load_dword v220, v[218:219], off
	s_add_i32 s43, s43, 0x100
	s_waitcnt vmcnt(6)
; __device__ __forceinline__ unsigned cvtpk(float lo, float hi) { f32x2_t v = {lo, hi}; bf16x2_t b = __builtin_convertvector(v, bf16x2_t); return __builtin_bit_cast(unsigned, b); }
; #define MFMA32(a, b, c) __builtin_amdgcn_mfma_f32_32x32x16_bf16((a), (b), (c), 0, 0, 0)
;     __device__ __forceinline__ bf16x8 vfrag(int kb, int c, int lane) const {
;         const int h = lane >> 5, dcol = 32 * c + (lane & 31);
;         float v[8];
; #pragma unroll
;         for (int i = 0; i < 8; ++i) v[i] = rowp(cv, nv, tile0 + 16 * kb + (i & 3) + 8 * (i >> 2) + 4 * h)[dcol];
;         u32x4 w; w.x = cvtpk(v[0], v[1]); w.y = cvtpk(v[2], v[3]); w.z = cvtpk(v[4], v[5]); w.w = cvtpk(v[6], v[7]);
;         return __builtin_bit_cast(bf16x8, w);
; template <class Prov, bool MASK>
; __device__ __forceinline__ void df_tile(const Prov& P, int comp, const bf16x8 (&qf)[4], int kv0, int kvlim, int lane, float& mx, float& ls, f32x16 (&o)[4]) {
;     ...
;     for (int kb = 0; kb < 4; ++kb) {
;         const int b2 = kb >> 1, r0 = 8 * (kb & 1);
;         u32x4 w; w.x = cvtpk(s[b2][r0], s[b2][r0 + 1]); w.y = cvtpk(s[b2][r0 + 2], s[b2][r0 + 3]); w.z = cvtpk(s[b2][r0 + 4], s[b2][r0 + 5]); w.w = cvtpk(s[b2][r0 + 6], s[b2][r0 + 7]);
;         const bf16x8 pf = __builtin_bit_cast(bf16x8, w);
; #pragma unroll
;         for (int c = 0; c < 4; ++c) o[c] = MFMA32(P.vfrag(kb, c, lane), pf, o[c]);
	v_cvt_pk_bf16_f32 v132, v130, v134
	s_waitcnt vmcnt(4)
	v_cvt_pk_bf16_f32 v133, v135, v171
	s_waitcnt vmcnt(2)
	v_cvt_pk_bf16_f32 v134, v173, v175
	v_mov_b32_e32 v173, v147
	s_waitcnt vmcnt(0)
	v_cvt_pk_bf16_f32 v135, v177, v220
	s_nop 1
	v_mfma_f32_32x32x16_bf16 v[48:63], v[132:135], v[64:67], v[48:63]
	v_lshl_add_u64 v[132:133], v[68:69], 0, v[172:173]
	global_load_dword v130, v[132:133], off
	v_lshl_add_u64 v[132:133], v[72:73], 0, v[172:173]
	global_load_dword v134, v[132:133], off
	v_lshl_add_u64 v[132:133], v[74:75], 0, v[172:173]
	global_load_dword v135, v[132:133], off
	v_lshl_add_u64 v[132:133], v[76:77], 0, v[172:173]
	global_load_dword v171, v[132:133], off
	v_lshl_add_u64 v[132:133], v[78:79], 0, v[172:173]
	global_load_dword v175, v[132:133], off
	v_lshl_add_u64 v[132:133], v[80:81], 0, v[172:173]
	global_load_dword v177, v[132:133], off
	v_lshl_add_u64 v[132:133], v[84:85], 0, v[172:173]
	global_load_dword v220, v[132:133], off
	v_lshl_add_u64 v[132:133], v[180:181], 0, v[172:173]
	global_load_dword v221, v[132:133], off
	s_waitcnt vmcnt(6)
	v_cvt_pk_bf16_f32 v132, v130, v134
	s_waitcnt vmcnt(4)
	v_cvt_pk_bf16_f32 v133, v135, v171
	s_waitcnt vmcnt(2)
	v_cvt_pk_bf16_f32 v134, v175, v177
	v_mov_b32_e32 v175, v147
	v_lshl_add_u64 v[68:69], v[68:69], 0, v[174:175]
	s_waitcnt vmcnt(0)
	v_cvt_pk_bf16_f32 v135, v220, v221
	s_nop 1
	v_mfma_f32_32x32x16_bf16 v[32:47], v[132:135], v[64:67], v[32:47]
	global_load_dword v70, v[70:71], off offset:256
	s_nop 0
	global_load_dword v71, v[82:83], off offset:256
	s_nop 0
	global_load_dword v82, v[86:87], off offset:256
	global_load_dword v83, v[136:137], off offset:256
	s_nop 0
	global_load_dword v86, v[138:139], off offset:256
	global_load_dword v87, v[140:141], off offset:256
	global_load_dword v130, v[142:143], off offset:256
	global_load_dword v135, v[218:219], off offset:256
	s_waitcnt vmcnt(6)
	v_cvt_pk_bf16_f32 v132, v70, v71
	global_load_dword v70, v[68:69], off
	v_lshl_add_u64 v[68:69], v[72:73], 0, v[174:175]
	global_load_dword v71, v[68:69], off
	v_lshl_add_u64 v[68:69], v[74:75], 0, v[174:175]
	global_load_dword v72, v[68:69], off
	v_lshl_add_u64 v[68:69], v[76:77], 0, v[174:175]
	global_load_dword v73, v[68:69], off
	v_lshl_add_u64 v[68:69], v[78:79], 0, v[174:175]
	global_load_dword v74, v[68:69], off
	v_lshl_add_u64 v[68:69], v[80:81], 0, v[174:175]
	global_load_dword v75, v[68:69], off
	v_lshl_add_u64 v[68:69], v[84:85], 0, v[174:175]
	global_load_dword v76, v[68:69], off
	v_lshl_add_u64 v[68:69], v[180:181], 0, v[174:175]
	global_load_dword v77, v[68:69], off
	s_waitcnt vmcnt(12)
	v_cvt_pk_bf16_f32 v133, v82, v83
	s_waitcnt vmcnt(10)
	v_cvt_pk_bf16_f32 v134, v86, v87
	s_waitcnt vmcnt(8)
	v_cvt_pk_bf16_f32 v135, v130, v135
	s_waitcnt vmcnt(6)
	v_cvt_pk_bf16_f32 v68, v70, v71
	v_mfma_f32_32x32x16_bf16 v[16:31], v[132:135], v[64:67], v[16:31]
	s_waitcnt vmcnt(4)
	v_cvt_pk_bf16_f32 v69, v72, v73
	v_add_u32_e32 v72, 17, v112
	v_add_u32_e32 v73, 0xfffff811, v112
	v_cndmask_b32_e32 v72, v72, v73, vcc
	s_waitcnt vmcnt(2)
	v_cvt_pk_bf16_f32 v70, v74, v75
	v_add_u32_e32 v74, 18, v112
	v_add_u32_e32 v75, 0xfffff812, v112
	v_cndmask_b32_e32 v74, v74, v75, vcc
	v_mov_b32_e32 v75, v147
	v_lshlrev_b64 v[74:75], 12, v[74:75]
	v_lshl_add_u64 v[80:81], s[6:7], 0, v[74:75]
	v_or_b32_e32 v74, 19, v131
	v_add_u32_e32 v75, 0xfffff800, v74
	s_waitcnt vmcnt(0)
	v_cvt_pk_bf16_f32 v71, v76, v77
	v_cndmask_b32_e32 v74, v74, v75, vcc
	v_mov_b32_e32 v75, v147
	v_lshlrev_b64 v[74:75], 12, v[74:75]
	v_lshl_add_u64 v[84:85], s[6:7], 0, v[74:75]
	v_add_u32_e32 v74, 24, v112
	v_add_u32_e32 v75, 0xfffff818, v112
	v_cndmask_b32_e32 v74, v74, v75, vcc
	v_mov_b32_e32 v75, v147
	v_lshlrev_b64 v[74:75], 12, v[74:75]
	v_mfma_f32_32x32x16_bf16 v[0:15], v[68:71], v[64:67], v[0:15]
	v_cvt_pk_bf16_f32 v64, v113, v114
	v_cvt_pk_bf16_f32 v65, v115, v125
	v_lshl_add_u64 v[114:115], s[6:7], 0, v[74:75]
	v_add_u32_e32 v74, 25, v112
	v_add_u32_e32 v75, 0xfffff819, v112
	v_cndmask_b32_e32 v74, v74, v75, vcc
	v_mov_b32_e32 v75, v147
	v_lshlrev_b64 v[74:75], 12, v[74:75]
	v_cvt_pk_bf16_f32 v67, v128, v129
	v_lshl_add_u64 v[128:129], s[6:7], 0, v[74:75]
	v_add_u32_e32 v74, 26, v112
	v_add_u32_e32 v75, 0xfffff81a, v112
	v_cndmask_b32_e32 v74, v74, v75, vcc
	v_mov_b32_e32 v75, v147
	v_lshlrev_b64 v[74:75], 12, v[74:75]
	v_add_u32_e32 v68, 16, v112
	v_add_u32_e32 v69, 0xfffff810, v112
	v_lshl_add_u64 v[112:113], s[6:7], 0, v[74:75]
	v_or_b32_e32 v74, 27, v131
	v_add_u32_e32 v75, 0xfffff800, v74
	v_cndmask_b32_e32 v68, v68, v69, vcc
	v_mov_b32_e32 v69, v147
	v_mov_b32_e32 v73, v147
	v_cndmask_b32_e32 v74, v74, v75, vcc
	v_mov_b32_e32 v75, v147
	v_lshlrev_b64 v[68:69], 12, v[68:69]
	v_lshlrev_b64 v[72:73], 12, v[72:73]
	v_lshlrev_b64 v[74:75], 12, v[74:75]
	v_lshl_add_u64 v[68:69], s[6:7], 0, v[68:69]
	v_lshl_add_u64 v[72:73], s[6:7], 0, v[72:73]
	v_lshl_add_u64 v[130:131], s[6:7], 0, v[74:75]
	v_cvt_pk_bf16_f32 v66, v126, v127
	v_lshl_add_u64 v[70:71], v[68:69], 0, v[146:147]
	v_lshl_add_u64 v[78:79], v[72:73], 0, v[146:147]
	v_lshl_add_u64 v[82:83], v[80:81], 0, v[146:147]
	v_lshl_add_u64 v[86:87], v[84:85], 0, v[146:147]
	v_lshl_add_u64 v[126:127], v[114:115], 0, v[146:147]
	v_lshl_add_u64 v[132:133], v[128:129], 0, v[146:147]
	v_lshl_add_u64 v[134:135], v[112:113], 0, v[146:147]
	v_lshl_add_u64 v[136:137], v[130:131], 0, v[146:147]
	global_load_dword v76, v[70:71], off
	global_load_dword v77, v[78:79], off
	global_load_dword v125, v[82:83], off
	global_load_dword v138, v[86:87], off
	global_load_dword v139, v[126:127], off
	global_load_dword v140, v[132:133], off
	global_load_dword v141, v[134:135], off
	global_load_dword v142, v[136:137], off
	s_waitcnt vmcnt(6)
; __device__ __forceinline__ unsigned cvtpk(float lo, float hi) { f32x2_t v = {lo, hi}; bf16x2_t b = __builtin_convertvector(v, bf16x2_t); return __builtin_bit_cast(unsigned, b); }
; #define MFMA32(a, b, c) __builtin_amdgcn_mfma_f32_32x32x16_bf16((a), (b), (c), 0, 0, 0)
;     __device__ __forceinline__ bf16x8 vfrag(int kb, int c, int lane) const {
;         const int h = lane >> 5, dcol = 32 * c + (lane & 31);
;         float v[8];
; #pragma unroll
;         for (int i = 0; i < 8; ++i) v[i] = rowp(cv, nv, tile0 + 16 * kb + (i & 3) + 8 * (i >> 2) + 4 * h)[dcol];
;         u32x4 w; w.x = cvtpk(v[0], v[1]); w.y = cvtpk(v[2], v[3]); w.z = cvtpk(v[4], v[5]); w.w = cvtpk(v[6], v[7]);
;         return __builtin_bit_cast(bf16x8, w);
; template <class Prov, bool MASK>
; __device__ __forceinline__ void df_tile(const Prov& P, int comp, const bf16x8 (&qf)[4], int kv0, int kvlim, int lane, float& mx, float& ls, f32x16 (&o)[4]) {
;     ...
;     for (int kb = 0; kb < 4; ++kb) {
;         const int b2 = kb >> 1, r0 = 8 * (kb & 1);
;         u32x4 w; w.x = cvtpk(s[b2][r0], s[b2][r0 + 1]); w.y = cvtpk(s[b2][r0 + 2], s[b2][r0 + 3]); w.z = cvtpk(s[b2][r0 + 4], s[b2][r0 + 5]); w.w = cvtpk(s[b2][r0 + 6], s[b2][r0 + 7]);
;         const bf16x8 pf = __builtin_bit_cast(bf16x8, w);
; #pragma unroll
;         for (int c = 0; c < 4; ++c) o[c] = MFMA32(P.vfrag(kb, c, lane), pf, o[c]);
	v_cvt_pk_bf16_f32 v74, v76, v77
	s_waitcnt vmcnt(4)
	v_cvt_pk_bf16_f32 v75, v125, v138
	s_waitcnt vmcnt(2)
	v_cvt_pk_bf16_f32 v76, v139, v140
	s_waitcnt vmcnt(0)
	v_cvt_pk_bf16_f32 v77, v141, v142
	s_nop 1
	v_mfma_f32_32x32x16_bf16 v[48:63], v[74:77], v[64:67], v[48:63]
	v_lshl_add_u64 v[74:75], v[68:69], 0, v[172:173]
	global_load_dword v76, v[74:75], off
	v_lshl_add_u64 v[74:75], v[72:73], 0, v[172:173]
	global_load_dword v77, v[74:75], off
	v_lshl_add_u64 v[74:75], v[80:81], 0, v[172:173]
	global_load_dword v125, v[74:75], off
	v_lshl_add_u64 v[74:75], v[84:85], 0, v[172:173]
	global_load_dword v138, v[74:75], off
	v_lshl_add_u64 v[74:75], v[114:115], 0, v[172:173]
	global_load_dword v139, v[74:75], off
	v_lshl_add_u64 v[74:75], v[128:129], 0, v[172:173]
	global_load_dword v140, v[74:75], off
	v_lshl_add_u64 v[74:75], v[112:113], 0, v[172:173]
	global_load_dword v141, v[74:75], off
	v_lshl_add_u64 v[74:75], v[130:131], 0, v[172:173]
	global_load_dword v142, v[74:75], off
	v_lshl_add_u64 v[68:69], v[68:69], 0, v[174:175]
	s_waitcnt vmcnt(6)
	v_cvt_pk_bf16_f32 v74, v76, v77
	s_waitcnt vmcnt(4)
	v_cvt_pk_bf16_f32 v75, v125, v138
	v_add_u32_e32 v125, s41, v209
	s_waitcnt vmcnt(2)
	v_cvt_pk_bf16_f32 v76, v139, v140
	s_waitcnt vmcnt(0)
	v_cvt_pk_bf16_f32 v77, v141, v142
	s_nop 1
	v_mfma_f32_32x32x16_bf16 v[32:47], v[74:77], v[64:67], v[32:47]
	global_load_dword v70, v[70:71], off offset:256
	s_nop 0
	global_load_dword v71, v[78:79], off offset:256
	global_load_dword v75, v[82:83], off offset:256
	global_load_dword v76, v[86:87], off offset:256
	global_load_dword v77, v[126:127], off offset:256
	s_nop 0
	global_load_dword v78, v[132:133], off offset:256
	global_load_dword v79, v[134:135], off offset:256
	global_load_dword v82, v[136:137], off offset:256
	v_mov_b32_e32 v83, v147
	s_waitcnt vmcnt(6)
	v_cvt_pk_bf16_f32 v74, v70, v71
	global_load_dword v70, v[68:69], off
	s_waitcnt vmcnt(5)
	v_cvt_pk_bf16_f32 v75, v75, v76
	v_lshl_add_u64 v[68:69], v[72:73], 0, v[174:175]
	s_waitcnt vmcnt(3)
	v_cvt_pk_bf16_f32 v76, v77, v78
	global_load_dword v71, v[68:69], off
	s_waitcnt vmcnt(2)
	v_cvt_pk_bf16_f32 v77, v79, v82
	v_lshl_add_u64 v[68:69], v[80:81], 0, v[174:175]
	global_load_dword v72, v[68:69], off
	v_lshl_add_u64 v[68:69], v[84:85], 0, v[174:175]
	global_load_dword v73, v[68:69], off
	v_lshl_add_u64 v[68:69], v[114:115], 0, v[174:175]
	v_mfma_f32_32x32x16_bf16 v[16:31], v[74:77], v[64:67], v[16:31]
	global_load_dword v74, v[68:69], off
	v_lshl_add_u64 v[68:69], v[128:129], 0, v[174:175]
	global_load_dword v75, v[68:69], off
	v_lshl_add_u64 v[68:69], v[112:113], 0, v[174:175]
	v_add_u32_e32 v112, s41, v211
	v_cndmask_b32_e32 v112, v112, v194, vcc
	v_mov_b32_e32 v113, v147
	v_lshl_add_u64 v[112:113], s[6:7], 0, v[112:113]
	v_lshl_add_u64 v[114:115], v[112:113], 0, v[146:147]
	global_load_dword v76, v[68:69], off
	global_load_dword v133, v[114:115], off
	v_lshl_add_u64 v[68:69], v[130:131], 0, v[174:175]
	global_load_dword v77, v[68:69], off
	v_add_u32_e32 v78, 0x28000, v125
	v_add_u32_e32 v82, 0x29000, v125
	v_cndmask_b32_e32 v78, v78, v194, vcc
	v_mov_b32_e32 v79, v147
	v_cndmask_b32_e32 v82, v82, v194, vcc
	v_lshl_add_u64 v[78:79], s[6:7], 0, v[78:79]
	v_lshl_add_u64 v[82:83], s[6:7], 0, v[82:83]
	s_waitcnt vmcnt(7)
	v_cvt_pk_bf16_f32 v68, v70, v71
	s_waitcnt vmcnt(5)
	v_cvt_pk_bf16_f32 v69, v72, v73
	v_add_u32_e32 v72, 0x22000, v125
	v_cndmask_b32_e32 v72, v72, v194, vcc
	v_mov_b32_e32 v73, v147
	v_lshl_add_u64 v[72:73], s[6:7], 0, v[72:73]
	s_waitcnt vmcnt(3)
	v_cvt_pk_bf16_f32 v70, v74, v75
	v_add_u32_e32 v74, s41, v212
	v_cndmask_b32_e32 v74, v74, v194, vcc
	v_mov_b32_e32 v75, v147
	v_lshl_add_u64 v[74:75], s[6:7], 0, v[74:75]
	v_lshl_add_u64 v[86:87], v[72:73], 0, v[146:147]
	v_lshl_add_u64 v[84:85], v[74:75], 0, v[146:147]
	global_load_dword v128, v[86:87], off
	s_waitcnt vmcnt(1)
	v_cvt_pk_bf16_f32 v71, v76, v77
	s_nop 1
	v_mfma_f32_32x32x16_bf16 v[0:15], v[68:71], v[64:67], v[0:15]
	v_cvt_pk_bf16_f32 v64, v88, v89
	v_add_u32_e32 v68, 0x20000, v125
	v_add_u32_e32 v70, 0x21000, v125
	v_add_u32_e32 v88, 0x2a000, v125
	v_cndmask_b32_e32 v68, v68, v194, vcc
	v_mov_b32_e32 v69, v147
	v_cndmask_b32_e32 v70, v70, v194, vcc
	v_mov_b32_e32 v71, v147
	v_cndmask_b32_e32 v88, v88, v194, vcc
	v_mov_b32_e32 v89, v147
	v_lshl_add_u64 v[68:69], s[6:7], 0, v[68:69]
	v_lshl_add_u64 v[70:71], s[6:7], 0, v[70:71]
	v_lshl_add_u64 v[88:89], s[6:7], 0, v[88:89]
	v_cvt_pk_bf16_f32 v65, v90, v91
	v_cvt_pk_bf16_f32 v66, v92, v93
	v_cvt_pk_bf16_f32 v67, v94, v95
	v_lshl_add_u64 v[76:77], v[68:69], 0, v[146:147]
	v_lshl_add_u64 v[80:81], v[70:71], 0, v[146:147]
	v_lshl_add_u64 v[90:91], v[78:79], 0, v[146:147]
	v_lshl_add_u64 v[92:93], v[82:83], 0, v[146:147]
	v_lshl_add_u64 v[94:95], v[88:89], 0, v[146:147]
	global_load_dword v126, v[76:77], off
	global_load_dword v127, v[80:81], off
	global_load_dword v130, v[90:91], off
	global_load_dword v131, v[92:93], off
	global_load_dword v132, v[94:95], off
	global_load_dword v129, v[84:85], off
	s_waitcnt vmcnt(4)
	v_cvt_pk_bf16_f32 v126, v126, v127
	s_waitcnt vmcnt(0)
; __device__ __forceinline__ unsigned cvtpk(float lo, float hi) { f32x2_t v = {lo, hi}; bf16x2_t b = __builtin_convertvector(v, bf16x2_t); return __builtin_bit_cast(unsigned, b); }
; #define MFMA32(a, b, c) __builtin_amdgcn_mfma_f32_32x32x16_bf16((a), (b), (c), 0, 0, 0)
;     __device__ __forceinline__ bf16x8 vfrag(int kb, int c, int lane) const {
;         const int h = lane >> 5, dcol = 32 * c + (lane & 31);
;         float v[8];
; #pragma unroll
;         for (int i = 0; i < 8; ++i) v[i] = rowp(cv, nv, tile0 + 16 * kb + (i & 3) + 8 * (i >> 2) + 4 * h)[dcol];
;         u32x4 w; w.x = cvtpk(v[0], v[1]); w.y = cvtpk(v[2], v[3]); w.z = cvtpk(v[4], v[5]); w.w = cvtpk(v[6], v[7]);
;         return __builtin_bit_cast(bf16x8, w);
; template <class Prov, bool MASK>
; __device__ __forceinline__ void df_tile(const Prov& P, int comp, const bf16x8 (&qf)[4], int kv0, int kvlim, int lane, float& mx, float& ls, f32x16 (&o)[4]) {
;     ...
;     for (int kb = 0; kb < 4; ++kb) {
;         const int b2 = kb >> 1, r0 = 8 * (kb & 1);
;         u32x4 w; w.x = cvtpk(s[b2][r0], s[b2][r0 + 1]); w.y = cvtpk(s[b2][r0 + 2], s[b2][r0 + 3]); w.z = cvtpk(s[b2][r0 + 4], s[b2][r0 + 5]); w.w = cvtpk(s[b2][r0 + 6], s[b2][r0 + 7]);
;         const bf16x8 pf = __builtin_bit_cast(bf16x8, w);
; #pragma unroll
;         for (int c = 0; c < 4; ++c) o[c] = MFMA32(P.vfrag(kb, c, lane), pf, o[c]);
;     }
	v_cvt_pk_bf16_f32 v127, v128, v129
	v_cvt_pk_bf16_f32 v128, v130, v131
	v_cvt_pk_bf16_f32 v129, v132, v133
	s_nop 1
	v_mfma_f32_32x32x16_bf16 v[48:63], v[126:129], v[64:67], v[48:63]
	v_lshl_add_u64 v[126:127], v[68:69], 0, v[172:173]
	global_load_dword v128, v[126:127], off
	v_lshl_add_u64 v[126:127], v[70:71], 0, v[172:173]
	global_load_dword v129, v[126:127], off
	v_lshl_add_u64 v[126:127], v[72:73], 0, v[172:173]
	global_load_dword v130, v[126:127], off
	v_lshl_add_u64 v[126:127], v[74:75], 0, v[172:173]
	global_load_dword v131, v[126:127], off
	v_lshl_add_u64 v[126:127], v[78:79], 0, v[172:173]
	global_load_dword v132, v[126:127], off
	v_lshl_add_u64 v[126:127], v[82:83], 0, v[172:173]
	global_load_dword v133, v[126:127], off
	v_lshl_add_u64 v[126:127], v[88:89], 0, v[172:173]
	global_load_dword v134, v[126:127], off
	v_lshl_add_u64 v[126:127], v[112:113], 0, v[172:173]
	global_load_dword v135, v[126:127], off
	s_nop 0
	global_load_dword v76, v[76:77], off offset:256
	s_nop 0
	global_load_dword v77, v[80:81], off offset:256
	s_nop 0
	global_load_dword v80, v[86:87], off offset:256
	global_load_dword v81, v[84:85], off offset:256
	s_nop 0
	global_load_dword v86, v[90:91], off offset:256
	global_load_dword v87, v[92:93], off offset:256
	s_nop 0
	global_load_dword v90, v[94:95], off offset:256
	global_load_dword v91, v[114:115], off offset:256
	v_lshl_add_u64 v[68:69], v[68:69], 0, v[174:175]
	s_waitcnt vmcnt(14)
	v_cvt_pk_bf16_f32 v126, v128, v129
	s_waitcnt vmcnt(12)
	v_cvt_pk_bf16_f32 v127, v130, v131
	s_waitcnt vmcnt(6)
	v_cvt_pk_bf16_f32 v84, v76, v77
	global_load_dword v76, v[68:69], off
	v_lshl_add_u64 v[68:69], v[70:71], 0, v[174:175]
	global_load_dword v70, v[68:69], off
	v_lshl_add_u64 v[68:69], v[72:73], 0, v[174:175]
	global_load_dword v71, v[68:69], off
	v_lshl_add_u64 v[68:69], v[74:75], 0, v[174:175]
	global_load_dword v72, v[68:69], off
	v_lshl_add_u64 v[68:69], v[78:79], 0, v[174:175]
	global_load_dword v73, v[68:69], off
	v_lshl_add_u64 v[68:69], v[82:83], 0, v[174:175]
	global_load_dword v74, v[68:69], off
	v_lshl_add_u64 v[68:69], v[88:89], 0, v[174:175]
	global_load_dword v75, v[68:69], off
	v_lshl_add_u64 v[68:69], v[112:113], 0, v[174:175]
	global_load_dword v77, v[68:69], off
	s_waitcnt vmcnt(12)
	v_cvt_pk_bf16_f32 v85, v80, v81
	s_waitcnt vmcnt(10)
	v_cvt_pk_bf16_f32 v86, v86, v87
	s_waitcnt vmcnt(8)
	v_cvt_pk_bf16_f32 v87, v90, v91
	v_cvt_pk_bf16_f32 v128, v132, v133
	v_cvt_pk_bf16_f32 v129, v134, v135
	v_add_u32_e32 v78, 0x39000, v125
	v_add_u32_e32 v80, 0x3a000, v125
	v_add_u32_e32 v82, s41, v208
	v_cndmask_b32_e32 v78, v78, v194, vcc
	v_mov_b32_e32 v79, v147
	v_cndmask_b32_e32 v80, v80, v194, vcc
	v_mov_b32_e32 v81, v147
	v_cndmask_b32_e32 v82, v82, v194, vcc
	v_mov_b32_e32 v83, v147
	v_lshl_add_u64 v[78:79], s[6:7], 0, v[78:79]
	v_lshl_add_u64 v[80:81], s[6:7], 0, v[80:81]
	v_lshl_add_u64 v[82:83], s[6:7], 0, v[82:83]
	v_mfma_f32_32x32x16_bf16 v[16:31], v[84:87], v[64:67], v[16:31]
	v_lshl_add_u64 v[112:113], v[78:79], 0, v[146:147]
	v_lshl_add_u64 v[114:115], v[80:81], 0, v[146:147]
	v_lshl_add_u64 v[86:87], v[82:83], 0, v[146:147]
	s_waitcnt vmcnt(6)
	v_cvt_pk_bf16_f32 v68, v76, v70
	v_add_u32_e32 v76, 0x38000, v125
	v_cndmask_b32_e32 v76, v76, v194, vcc
	v_mfma_f32_32x32x16_bf16 v[32:47], v[126:129], v[64:67], v[32:47]
	s_waitcnt vmcnt(4)
	v_cvt_pk_bf16_f32 v69, v71, v72
	v_add_u32_e32 v72, 0x32000, v125
	v_cndmask_b32_e32 v72, v72, v194, vcc
	s_waitcnt vmcnt(2)
	v_cvt_pk_bf16_f32 v70, v73, v74
	v_add_u32_e32 v74, s41, v210
	v_mov_b32_e32 v73, v147
	v_cndmask_b32_e32 v74, v74, v194, vcc
	s_waitcnt vmcnt(0)
	v_cvt_pk_bf16_f32 v71, v75, v77
	v_mov_b32_e32 v75, v147
	v_mov_b32_e32 v77, v147
	v_mfma_f32_32x32x16_bf16 v[0:15], v[68:71], v[64:67], v[0:15]
	v_add_u32_e32 v68, 0x30000, v125
	v_add_u32_e32 v70, 0x31000, v125
	v_cndmask_b32_e32 v68, v68, v194, vcc
	v_mov_b32_e32 v69, v147
	v_cndmask_b32_e32 v70, v70, v194, vcc
	v_mov_b32_e32 v71, v147
	v_lshl_add_u64 v[68:69], s[6:7], 0, v[68:69]
	v_lshl_add_u64 v[70:71], s[6:7], 0, v[70:71]
	v_lshl_add_u64 v[72:73], s[6:7], 0, v[72:73]
	v_lshl_add_u64 v[74:75], s[6:7], 0, v[74:75]
	v_lshl_add_u64 v[76:77], s[6:7], 0, v[76:77]
	v_lshl_add_u64 v[84:85], v[68:69], 0, v[146:147]
	v_lshl_add_u64 v[88:89], v[70:71], 0, v[146:147]
	v_lshl_add_u64 v[92:93], v[72:73], 0, v[146:147]
	v_lshl_add_u64 v[90:91], v[74:75], 0, v[146:147]
	v_lshl_add_u64 v[94:95], v[76:77], 0, v[146:147]
	v_cvt_pk_bf16_f32 v64, v117, v118
	v_cvt_pk_bf16_f32 v65, v119, v120
	v_cvt_pk_bf16_f32 v66, v121, v122
	v_cvt_pk_bf16_f32 v67, v123, v124
	global_load_dword v117, v[84:85], off
	global_load_dword v118, v[88:89], off
	global_load_dword v119, v[92:93], off
	global_load_dword v121, v[94:95], off
	global_load_dword v122, v[112:113], off
	global_load_dword v123, v[114:115], off
	global_load_dword v120, v[90:91], off
	global_load_dword v124, v[86:87], off
	s_add_i32 s41, s41, 0x100000
	s_cmpk_ge_i32 s43, 0x840
	s_waitcnt vmcnt(6)
	v_cvt_pk_bf16_f32 v118, v117, v118
	s_waitcnt vmcnt(1)
	v_cvt_pk_bf16_f32 v119, v119, v120
	v_cvt_pk_bf16_f32 v120, v121, v122
	s_waitcnt vmcnt(0)
; __device__ __forceinline__ unsigned cvtpk(float lo, float hi) { f32x2_t v = {lo, hi}; bf16x2_t b = __builtin_convertvector(v, bf16x2_t); return __builtin_bit_cast(unsigned, b); }
; #define MFMA32(a, b, c) __builtin_amdgcn_mfma_f32_32x32x16_bf16((a), (b), (c), 0, 0, 0)
; template <class Prov, bool MASK>
; __device__ __forceinline__ void df_tile(const Prov& P, int comp, const bf16x8 (&qf)[4], int kv0, int kvlim, int lane, float& mx, float& ls, f32x16 (&o)[4]) {
;     ...
;     for (int kb = 0; kb < 4; ++kb) {
;         const int b2 = kb >> 1, r0 = 8 * (kb & 1);
;         u32x4 w; w.x = cvtpk(s[b2][r0], s[b2][r0 + 1]); w.y = cvtpk(s[b2][r0 + 2], s[b2][r0 + 3]); w.z = cvtpk(s[b2][r0 + 4], s[b2][r0 + 5]); w.w = cvtpk(s[b2][r0 + 6], s[b2][r0 + 7]);
;         const bf16x8 pf = __builtin_bit_cast(bf16x8, w);
; #pragma unroll
;         for (int c = 0; c < 4; ++c) o[c] = MFMA32(P.vfrag(kb, c, lane), pf, o[c]);
;     }
; __device__ __forceinline__ void df_attn_phase(int j, float lambda_init, LAS unsigned char* lds, unsigned* ctr) {
;     ...
;             for (int t = 0; t <= 32; ++t) { G.tile0 = 64 * t; df_tile<GlbProv, true>(G, comp, qf, 64 * t, PAST + 32, lane, mx, ls, o); }
	v_cvt_pk_bf16_f32 v121, v123, v124
	s_nop 1
	v_mfma_f32_32x32x16_bf16 v[48:63], v[118:121], v[64:67], v[48:63]
	v_lshl_add_u64 v[118:119], v[68:69], 0, v[172:173]
	global_load_dword v117, v[118:119], off
	v_lshl_add_u64 v[118:119], v[70:71], 0, v[172:173]
	global_load_dword v120, v[118:119], off
	v_lshl_add_u64 v[118:119], v[72:73], 0, v[172:173]
	global_load_dword v121, v[118:119], off
	v_lshl_add_u64 v[118:119], v[74:75], 0, v[172:173]
	global_load_dword v122, v[118:119], off
	v_lshl_add_u64 v[118:119], v[76:77], 0, v[172:173]
	global_load_dword v123, v[118:119], off
	v_lshl_add_u64 v[118:119], v[78:79], 0, v[172:173]
	global_load_dword v124, v[118:119], off
	v_lshl_add_u64 v[118:119], v[80:81], 0, v[172:173]
	global_load_dword v125, v[118:119], off
	v_lshl_add_u64 v[118:119], v[82:83], 0, v[172:173]
	global_load_dword v126, v[118:119], off
	s_nop 0
	global_load_dword v84, v[84:85], off offset:256
	s_nop 0
	global_load_dword v85, v[88:89], off offset:256
	s_nop 0
	global_load_dword v88, v[92:93], off offset:256
	global_load_dword v89, v[90:91], off offset:256
	s_nop 0
	global_load_dword v90, v[94:95], off offset:256
	global_load_dword v91, v[112:113], off offset:256
	global_load_dword v92, v[114:115], off offset:256
	s_nop 0
	global_load_dword v87, v[86:87], off offset:256
	v_lshl_add_u64 v[68:69], v[68:69], 0, v[174:175]
	v_mov_b32_e32 v113, v116
	s_waitcnt vmcnt(14)
	v_cvt_pk_bf16_f32 v118, v117, v120
	s_waitcnt vmcnt(12)
	v_cvt_pk_bf16_f32 v119, v121, v122
	s_waitcnt vmcnt(6)
	v_cvt_pk_bf16_f32 v84, v84, v85
	v_cvt_pk_bf16_f32 v120, v123, v124
	s_waitcnt vmcnt(4)
	v_cvt_pk_bf16_f32 v85, v88, v89
	s_waitcnt vmcnt(2)
	v_cvt_pk_bf16_f32 v86, v90, v91
	v_cvt_pk_bf16_f32 v121, v125, v126
	s_waitcnt vmcnt(0)
	v_cvt_pk_bf16_f32 v87, v92, v87
	v_mfma_f32_32x32x16_bf16 v[32:47], v[118:121], v[64:67], v[32:47]
	s_nop 0
	v_mfma_f32_32x32x16_bf16 v[16:31], v[84:87], v[64:67], v[16:31]
	global_load_dword v84, v[68:69], off
	v_lshl_add_u64 v[68:69], v[70:71], 0, v[174:175]
	global_load_dword v70, v[68:69], off
	v_lshl_add_u64 v[68:69], v[72:73], 0, v[174:175]
	global_load_dword v71, v[68:69], off
	v_lshl_add_u64 v[68:69], v[74:75], 0, v[174:175]
	global_load_dword v72, v[68:69], off
	v_lshl_add_u64 v[68:69], v[76:77], 0, v[174:175]
	global_load_dword v73, v[68:69], off
	v_lshl_add_u64 v[68:69], v[78:79], 0, v[174:175]
	global_load_dword v74, v[68:69], off
	v_lshl_add_u64 v[68:69], v[80:81], 0, v[174:175]
	global_load_dword v75, v[68:69], off
	v_lshl_add_u64 v[68:69], v[82:83], 0, v[174:175]
	global_load_dword v76, v[68:69], off
	s_waitcnt vmcnt(6)
	v_cvt_pk_bf16_f32 v68, v84, v70
	s_waitcnt vmcnt(4)
	v_cvt_pk_bf16_f32 v69, v71, v72
	s_waitcnt vmcnt(2)
	v_cvt_pk_bf16_f32 v70, v73, v74
	s_waitcnt vmcnt(0)
	v_cvt_pk_bf16_f32 v71, v75, v76
	s_nop 1
	v_mfma_f32_32x32x16_bf16 v[0:15], v[68:71], v[64:67], v[0:15]
	s_cbranch_scc0 .LBB0_275
	s_nop 15
	s_lshr_b32 s100, s22, 4
	s_add_i32 s98, s100, s13
	s_mul_i32 s99, s98, 0x4200
	s_mul_i32 s100, s100, 0x4200
	s_addk_i32 s99, 0x100
	s_addk_i32 s100, 0x100
	v_lshl_add_u32 v221, v190, 2, s99
	v_lshl_add_u32 v222, v190, 2, s100
	ds_write2st64_b32 v221, v0, v1 offset0:0 offset1:1
	ds_write2st64_b32 v221, v2, v3 offset0:2 offset1:3
	ds_write2st64_b32 v221, v4, v5 offset0:4 offset1:5
	ds_write2st64_b32 v221, v6, v7 offset0:6 offset1:7
	ds_write2st64_b32 v221, v8, v9 offset0:8 offset1:9
	ds_write2st64_b32 v221, v10, v11 offset0:10 offset1:11
	ds_write2st64_b32 v221, v12, v13 offset0:12 offset1:13
	ds_write2st64_b32 v221, v14, v15 offset0:14 offset1:15
	ds_write2st64_b32 v221, v16, v17 offset0:16 offset1:17
	ds_write2st64_b32 v221, v18, v19 offset0:18 offset1:19
	ds_write2st64_b32 v221, v20, v21 offset0:20 offset1:21
	ds_write2st64_b32 v221, v22, v23 offset0:22 offset1:23
	ds_write2st64_b32 v221, v24, v25 offset0:24 offset1:25
	ds_write2st64_b32 v221, v26, v27 offset0:26 offset1:27
	ds_write2st64_b32 v221, v28, v29 offset0:28 offset1:29
	ds_write2st64_b32 v221, v30, v31 offset0:30 offset1:31
	ds_write2st64_b32 v221, v32, v33 offset0:32 offset1:33
	ds_write2st64_b32 v221, v34, v35 offset0:34 offset1:35
	ds_write2st64_b32 v221, v36, v37 offset0:36 offset1:37
	ds_write2st64_b32 v221, v38, v39 offset0:38 offset1:39
	ds_write2st64_b32 v221, v40, v41 offset0:40 offset1:41
	ds_write2st64_b32 v221, v42, v43 offset0:42 offset1:43
	ds_write2st64_b32 v221, v44, v45 offset0:44 offset1:45
	ds_write2st64_b32 v221, v46, v47 offset0:46 offset1:47
	ds_write2st64_b32 v221, v48, v49 offset0:48 offset1:49
	ds_write2st64_b32 v221, v50, v51 offset0:50 offset1:51
	ds_write2st64_b32 v221, v52, v53 offset0:52 offset1:53
	ds_write2st64_b32 v221, v54, v55 offset0:54 offset1:55
	ds_write2st64_b32 v221, v56, v57 offset0:56 offset1:57
	ds_write2st64_b32 v221, v58, v59 offset0:58 offset1:59
	ds_write2st64_b32 v221, v60, v61 offset0:60 offset1:61
	ds_write2st64_b32 v221, v62, v63 offset0:62 offset1:63
	ds_write2st64_b32 v221, v113, v169 offset0:64 offset1:65
	s_waitcnt lgkmcnt(0)
	s_barrier
; template <class Prov, bool MASK>
; __device__ __forceinline__ void df_tile(const Prov& P, int comp, const bf16x8 (&qf)[4], int kv0, int kvlim, int lane, float& mx, float& ls, f32x16 (&o)[4]) {
;     ...
;     const float mn = fmaxf(mx, m), al = __builtin_amdgcn_exp2f(mx - mn);
;     mx = mn;
;     float ps = 0.f;
; #pragma unroll
;     for (int b2 = 0; b2 < 2; ++b2)
; #pragma unroll
;         for (int r = 0; r < 16; ++r) { const float p = __builtin_amdgcn_exp2f(s[b2][r] - mn); s[b2][r] = p; ps += p; }
;     ls = ls * al + ps;
; #pragma unroll
;     for (int c = 0; c < 4; ++c) o[c] = o[c] * al;
	ds_read2st64_b32 v[72:73], v222 offset0:0 offset1:1
	ds_read2st64_b32 v[74:75], v222 offset0:2 offset1:3
	ds_read2st64_b32 v[76:77], v222 offset0:4 offset1:5
	ds_read2st64_b32 v[78:79], v222 offset0:6 offset1:7
	ds_read2st64_b32 v[80:81], v222 offset0:8 offset1:9
	ds_read2st64_b32 v[82:83], v222 offset0:10 offset1:11
	ds_read2st64_b32 v[84:85], v222 offset0:12 offset1:13
	ds_read2st64_b32 v[86:87], v222 offset0:14 offset1:15
	ds_read2st64_b32 v[88:89], v222 offset0:16 offset1:17
	ds_read2st64_b32 v[90:91], v222 offset0:18 offset1:19
	ds_read2st64_b32 v[92:93], v222 offset0:20 offset1:21
	ds_read2st64_b32 v[94:95], v222 offset0:22 offset1:23
	ds_read2st64_b32 v[96:97], v222 offset0:24 offset1:25
	ds_read2st64_b32 v[98:99], v222 offset0:26 offset1:27
	ds_read2st64_b32 v[100:101], v222 offset0:28 offset1:29
	ds_read2st64_b32 v[102:103], v222 offset0:30 offset1:31
	ds_read2st64_b32 v[104:105], v222 offset0:32 offset1:33
	ds_read2st64_b32 v[108:109], v222 offset0:34 offset1:35
	ds_read2st64_b32 v[110:111], v222 offset0:36 offset1:37
	ds_read2st64_b32 v[112:113], v222 offset0:38 offset1:39
	ds_read2st64_b32 v[114:115], v222 offset0:40 offset1:41
	ds_read2st64_b32 v[116:117], v222 offset0:42 offset1:43
	ds_read2st64_b32 v[118:119], v222 offset0:44 offset1:45
	ds_read2st64_b32 v[120:121], v222 offset0:46 offset1:47
	ds_read2st64_b32 v[122:123], v222 offset0:48 offset1:49
	ds_read2st64_b32 v[124:125], v222 offset0:50 offset1:51
	ds_read2st64_b32 v[126:127], v222 offset0:52 offset1:53
	ds_read2st64_b32 v[128:129], v222 offset0:54 offset1:55
	ds_read2st64_b32 v[130:131], v222 offset0:56 offset1:57
	ds_read2st64_b32 v[132:133], v222 offset0:58 offset1:59
	ds_read2st64_b32 v[134:135], v222 offset0:60 offset1:61
	ds_read2st64_b32 v[136:137], v222 offset0:62 offset1:63
	ds_read2st64_b32 v[138:139], v222 offset0:64 offset1:65
	v_add_u32_e32 v222, 0x4200, v222
	s_waitcnt lgkmcnt(0)
	v_mov_b32_e32 v0, v72
	v_mov_b32_e32 v1, v73
	v_mov_b32_e32 v2, v74
	v_mov_b32_e32 v3, v75
	v_mov_b32_e32 v4, v76
	v_mov_b32_e32 v5, v77
	v_mov_b32_e32 v6, v78
	v_mov_b32_e32 v7, v79
	v_mov_b32_e32 v8, v80
	v_mov_b32_e32 v9, v81
	v_mov_b32_e32 v10, v82
	v_mov_b32_e32 v11, v83
	v_mov_b32_e32 v12, v84
	v_mov_b32_e32 v13, v85
	v_mov_b32_e32 v14, v86
	v_mov_b32_e32 v15, v87
	v_mov_b32_e32 v16, v88
	v_mov_b32_e32 v17, v89
	v_mov_b32_e32 v18, v90
	v_mov_b32_e32 v19, v91
	v_mov_b32_e32 v20, v92
	v_mov_b32_e32 v21, v93
	v_mov_b32_e32 v22, v94
	v_mov_b32_e32 v23, v95
	v_mov_b32_e32 v24, v96
	v_mov_b32_e32 v25, v97
	v_mov_b32_e32 v26, v98
	v_mov_b32_e32 v27, v99
	v_mov_b32_e32 v28, v100
	v_mov_b32_e32 v29, v101
	v_mov_b32_e32 v30, v102
	v_mov_b32_e32 v31, v103
	v_mov_b32_e32 v32, v104
	v_mov_b32_e32 v33, v105
	v_mov_b32_e32 v34, v108
	v_mov_b32_e32 v35, v109
	v_mov_b32_e32 v36, v110
	v_mov_b32_e32 v37, v111
	v_mov_b32_e32 v38, v112
	v_mov_b32_e32 v39, v113
	v_mov_b32_e32 v40, v114
	v_mov_b32_e32 v41, v115
	v_mov_b32_e32 v42, v116
	v_mov_b32_e32 v43, v117
	v_mov_b32_e32 v44, v118
	v_mov_b32_e32 v45, v119
	v_mov_b32_e32 v46, v120
	v_mov_b32_e32 v47, v121
	v_mov_b32_e32 v48, v122
	v_mov_b32_e32 v49, v123
	v_mov_b32_e32 v50, v124
	v_mov_b32_e32 v51, v125
	v_mov_b32_e32 v52, v126
	v_mov_b32_e32 v53, v127
	v_mov_b32_e32 v54, v128
	v_mov_b32_e32 v55, v129
	v_mov_b32_e32 v56, v130
	v_mov_b32_e32 v57, v131
	v_mov_b32_e32 v58, v132
	v_mov_b32_e32 v59, v133
	v_mov_b32_e32 v60, v134
	v_mov_b32_e32 v61, v135
	v_mov_b32_e32 v62, v136
	v_mov_b32_e32 v63, v137
	v_mov_b32_e32 v218, v138
	v_mov_b32_e32 v169, v139
	ds_read2st64_b32 v[72:73], v222 offset0:0 offset1:1
	ds_read2st64_b32 v[74:75], v222 offset0:2 offset1:3
	ds_read2st64_b32 v[76:77], v222 offset0:4 offset1:5
	ds_read2st64_b32 v[78:79], v222 offset0:6 offset1:7
	ds_read2st64_b32 v[80:81], v222 offset0:8 offset1:9
	ds_read2st64_b32 v[82:83], v222 offset0:10 offset1:11
	ds_read2st64_b32 v[84:85], v222 offset0:12 offset1:13
	ds_read2st64_b32 v[86:87], v222 offset0:14 offset1:15
	ds_read2st64_b32 v[88:89], v222 offset0:16 offset1:17
	ds_read2st64_b32 v[90:91], v222 offset0:18 offset1:19
	ds_read2st64_b32 v[92:93], v222 offset0:20 offset1:21
	ds_read2st64_b32 v[94:95], v222 offset0:22 offset1:23
	ds_read2st64_b32 v[96:97], v222 offset0:24 offset1:25
	ds_read2st64_b32 v[98:99], v222 offset0:26 offset1:27
	ds_read2st64_b32 v[100:101], v222 offset0:28 offset1:29
	ds_read2st64_b32 v[102:103], v222 offset0:30 offset1:31
	ds_read2st64_b32 v[104:105], v222 offset0:32 offset1:33
	ds_read2st64_b32 v[108:109], v222 offset0:34 offset1:35
	ds_read2st64_b32 v[110:111], v222 offset0:36 offset1:37
	ds_read2st64_b32 v[112:113], v222 offset0:38 offset1:39
	ds_read2st64_b32 v[114:115], v222 offset0:40 offset1:41
	ds_read2st64_b32 v[116:117], v222 offset0:42 offset1:43
	ds_read2st64_b32 v[118:119], v222 offset0:44 offset1:45
	ds_read2st64_b32 v[120:121], v222 offset0:46 offset1:47
	ds_read2st64_b32 v[122:123], v222 offset0:48 offset1:49
	ds_read2st64_b32 v[124:125], v222 offset0:50 offset1:51
	ds_read2st64_b32 v[126:127], v222 offset0:52 offset1:53
	ds_read2st64_b32 v[128:129], v222 offset0:54 offset1:55
	ds_read2st64_b32 v[130:131], v222 offset0:56 offset1:57
	ds_read2st64_b32 v[132:133], v222 offset0:58 offset1:59
	ds_read2st64_b32 v[134:135], v222 offset0:60 offset1:61
	ds_read2st64_b32 v[136:137], v222 offset0:62 offset1:63
	ds_read2st64_b32 v[138:139], v222 offset0:64 offset1:65
	v_add_u32_e32 v222, 0x4200, v222
	s_waitcnt lgkmcnt(0)
; template <class Prov, bool MASK>
; __device__ __forceinline__ void df_tile(const Prov& P, int comp, const bf16x8 (&qf)[4], int kv0, int kvlim, int lane, float& mx, float& ls, f32x16 (&o)[4]) {
;     ...
;     const float mn = fmaxf(mx, m), al = __builtin_amdgcn_exp2f(mx - mn);
;     mx = mn;
;     float ps = 0.f;
; #pragma unroll
;     for (int b2 = 0; b2 < 2; ++b2)
; #pragma unroll
;         for (int r = 0; r < 16; ++r) { const float p = __builtin_amdgcn_exp2f(s[b2][r] - mn); s[b2][r] = p; ps += p; }
;     ls = ls * al + ps;
; #pragma unroll
;     for (int c = 0; c < 4; ++c) o[c] = o[c] * al;
	v_max_f32_e32 v223, v218, v138
	v_sub_f32_e32 v219, v218, v223
	v_sub_f32_e32 v220, v138, v223
	v_exp_f32_e32 v219, v219
	v_exp_f32_e32 v220, v220
	v_mov_b32_e32 v218, v223
	v_mul_f32_e32 v169, v169, v219
	v_fmac_f32_e32 v169, v139, v220
	v_mul_f32_e32 v0, v0, v219
	v_mul_f32_e32 v1, v1, v219
	v_mul_f32_e32 v2, v2, v219
	v_mul_f32_e32 v3, v3, v219
	v_mul_f32_e32 v4, v4, v219
	v_mul_f32_e32 v5, v5, v219
	v_mul_f32_e32 v6, v6, v219
	v_mul_f32_e32 v7, v7, v219
	v_mul_f32_e32 v8, v8, v219
	v_mul_f32_e32 v9, v9, v219
	v_mul_f32_e32 v10, v10, v219
	v_mul_f32_e32 v11, v11, v219
	v_mul_f32_e32 v12, v12, v219
	v_mul_f32_e32 v13, v13, v219
	v_mul_f32_e32 v14, v14, v219
	v_mul_f32_e32 v15, v15, v219
	v_mul_f32_e32 v16, v16, v219
	v_mul_f32_e32 v17, v17, v219
	v_mul_f32_e32 v18, v18, v219
	v_mul_f32_e32 v19, v19, v219
	v_mul_f32_e32 v20, v20, v219
	v_mul_f32_e32 v21, v21, v219
	v_mul_f32_e32 v22, v22, v219
	v_mul_f32_e32 v23, v23, v219
	v_mul_f32_e32 v24, v24, v219
	v_mul_f32_e32 v25, v25, v219
	v_mul_f32_e32 v26, v26, v219
	v_mul_f32_e32 v27, v27, v219
	v_mul_f32_e32 v28, v28, v219
	v_mul_f32_e32 v29, v29, v219
	v_mul_f32_e32 v30, v30, v219
	v_mul_f32_e32 v31, v31, v219
	v_mul_f32_e32 v32, v32, v219
	v_mul_f32_e32 v33, v33, v219
	v_mul_f32_e32 v34, v34, v219
	v_mul_f32_e32 v35, v35, v219
	v_mul_f32_e32 v36, v36, v219
	v_mul_f32_e32 v37, v37, v219
	v_mul_f32_e32 v38, v38, v219
	v_mul_f32_e32 v39, v39, v219
	v_mul_f32_e32 v40, v40, v219
	v_mul_f32_e32 v41, v41, v219
	v_mul_f32_e32 v42, v42, v219
	v_mul_f32_e32 v43, v43, v219
	v_mul_f32_e32 v44, v44, v219
	v_mul_f32_e32 v45, v45, v219
	v_mul_f32_e32 v46, v46, v219
	v_mul_f32_e32 v47, v47, v219
	v_mul_f32_e32 v48, v48, v219
	v_mul_f32_e32 v49, v49, v219
	v_mul_f32_e32 v50, v50, v219
	v_mul_f32_e32 v51, v51, v219
	v_mul_f32_e32 v52, v52, v219
	v_mul_f32_e32 v53, v53, v219
	v_mul_f32_e32 v54, v54, v219
	v_mul_f32_e32 v55, v55, v219
	v_mul_f32_e32 v56, v56, v219
	v_mul_f32_e32 v57, v57, v219
	v_mul_f32_e32 v58, v58, v219
	v_mul_f32_e32 v59, v59, v219
	v_mul_f32_e32 v60, v60, v219
	v_mul_f32_e32 v61, v61, v219
	v_mul_f32_e32 v62, v62, v219
	v_mul_f32_e32 v63, v63, v219
	v_fmac_f32_e32 v0, v72, v220
	v_fmac_f32_e32 v1, v73, v220
	v_fmac_f32_e32 v2, v74, v220
	v_fmac_f32_e32 v3, v75, v220
	v_fmac_f32_e32 v4, v76, v220
	v_fmac_f32_e32 v5, v77, v220
	v_fmac_f32_e32 v6, v78, v220
	v_fmac_f32_e32 v7, v79, v220
	v_fmac_f32_e32 v8, v80, v220
	v_fmac_f32_e32 v9, v81, v220
	v_fmac_f32_e32 v10, v82, v220
	v_fmac_f32_e32 v11, v83, v220
	v_fmac_f32_e32 v12, v84, v220
	v_fmac_f32_e32 v13, v85, v220
	v_fmac_f32_e32 v14, v86, v220
	v_fmac_f32_e32 v15, v87, v220
	v_fmac_f32_e32 v16, v88, v220
	v_fmac_f32_e32 v17, v89, v220
	v_fmac_f32_e32 v18, v90, v220
	v_fmac_f32_e32 v19, v91, v220
	v_fmac_f32_e32 v20, v92, v220
	v_fmac_f32_e32 v21, v93, v220
	v_fmac_f32_e32 v22, v94, v220
	v_fmac_f32_e32 v23, v95, v220
	v_fmac_f32_e32 v24, v96, v220
	v_fmac_f32_e32 v25, v97, v220
	v_fmac_f32_e32 v26, v98, v220
	v_fmac_f32_e32 v27, v99, v220
	v_fmac_f32_e32 v28, v100, v220
	v_fmac_f32_e32 v29, v101, v220
	v_fmac_f32_e32 v30, v102, v220
	v_fmac_f32_e32 v31, v103, v220
	v_fmac_f32_e32 v32, v104, v220
	v_fmac_f32_e32 v33, v105, v220
	v_fmac_f32_e32 v34, v108, v220
	v_fmac_f32_e32 v35, v109, v220
	v_fmac_f32_e32 v36, v110, v220
	v_fmac_f32_e32 v37, v111, v220
	v_fmac_f32_e32 v38, v112, v220
	v_fmac_f32_e32 v39, v113, v220
	v_fmac_f32_e32 v40, v114, v220
	v_fmac_f32_e32 v41, v115, v220
	v_fmac_f32_e32 v42, v116, v220
	v_fmac_f32_e32 v43, v117, v220
	v_fmac_f32_e32 v44, v118, v220
	v_fmac_f32_e32 v45, v119, v220
	v_fmac_f32_e32 v46, v120, v220
	v_fmac_f32_e32 v47, v121, v220
	v_fmac_f32_e32 v48, v122, v220
	v_fmac_f32_e32 v49, v123, v220
	v_fmac_f32_e32 v50, v124, v220
	v_fmac_f32_e32 v51, v125, v220
	v_fmac_f32_e32 v52, v126, v220
	v_fmac_f32_e32 v53, v127, v220
	v_fmac_f32_e32 v54, v128, v220
	v_fmac_f32_e32 v55, v129, v220
	v_fmac_f32_e32 v56, v130, v220
	v_fmac_f32_e32 v57, v131, v220
	v_fmac_f32_e32 v58, v132, v220
	v_fmac_f32_e32 v59, v133, v220
	v_fmac_f32_e32 v60, v134, v220
	v_fmac_f32_e32 v61, v135, v220
	v_fmac_f32_e32 v62, v136, v220
	v_fmac_f32_e32 v63, v137, v220
	ds_read2st64_b32 v[72:73], v222 offset0:0 offset1:1
	ds_read2st64_b32 v[74:75], v222 offset0:2 offset1:3
	ds_read2st64_b32 v[76:77], v222 offset0:4 offset1:5
	ds_read2st64_b32 v[78:79], v222 offset0:6 offset1:7
	ds_read2st64_b32 v[80:81], v222 offset0:8 offset1:9
	ds_read2st64_b32 v[82:83], v222 offset0:10 offset1:11
	ds_read2st64_b32 v[84:85], v222 offset0:12 offset1:13
	ds_read2st64_b32 v[86:87], v222 offset0:14 offset1:15
	ds_read2st64_b32 v[88:89], v222 offset0:16 offset1:17
	ds_read2st64_b32 v[90:91], v222 offset0:18 offset1:19
	ds_read2st64_b32 v[92:93], v222 offset0:20 offset1:21
	ds_read2st64_b32 v[94:95], v222 offset0:22 offset1:23
	ds_read2st64_b32 v[96:97], v222 offset0:24 offset1:25
	ds_read2st64_b32 v[98:99], v222 offset0:26 offset1:27
	ds_read2st64_b32 v[100:101], v222 offset0:28 offset1:29
	ds_read2st64_b32 v[102:103], v222 offset0:30 offset1:31
	ds_read2st64_b32 v[104:105], v222 offset0:32 offset1:33
	ds_read2st64_b32 v[108:109], v222 offset0:34 offset1:35
	ds_read2st64_b32 v[110:111], v222 offset0:36 offset1:37
	ds_read2st64_b32 v[112:113], v222 offset0:38 offset1:39
	ds_read2st64_b32 v[114:115], v222 offset0:40 offset1:41
	ds_read2st64_b32 v[116:117], v222 offset0:42 offset1:43
	ds_read2st64_b32 v[118:119], v222 offset0:44 offset1:45
	ds_read2st64_b32 v[120:121], v222 offset0:46 offset1:47
	ds_read2st64_b32 v[122:123], v222 offset0:48 offset1:49
	ds_read2st64_b32 v[124:125], v222 offset0:50 offset1:51
	ds_read2st64_b32 v[126:127], v222 offset0:52 offset1:53
	ds_read2st64_b32 v[128:129], v222 offset0:54 offset1:55
	ds_read2st64_b32 v[130:131], v222 offset0:56 offset1:57
	ds_read2st64_b32 v[132:133], v222 offset0:58 offset1:59
	ds_read2st64_b32 v[134:135], v222 offset0:60 offset1:61
	ds_read2st64_b32 v[136:137], v222 offset0:62 offset1:63
	ds_read2st64_b32 v[138:139], v222 offset0:64 offset1:65
	v_add_u32_e32 v222, 0x4200, v222
	s_waitcnt lgkmcnt(0)
; template <class Prov, bool MASK>
; __device__ __forceinline__ void df_tile(const Prov& P, int comp, const bf16x8 (&qf)[4], int kv0, int kvlim, int lane, float& mx, float& ls, f32x16 (&o)[4]) {
;     ...
;     const float mn = fmaxf(mx, m), al = __builtin_amdgcn_exp2f(mx - mn);
;     mx = mn;
;     float ps = 0.f;
; #pragma unroll
;     for (int b2 = 0; b2 < 2; ++b2)
; #pragma unroll
;         for (int r = 0; r < 16; ++r) { const float p = __builtin_amdgcn_exp2f(s[b2][r] - mn); s[b2][r] = p; ps += p; }
;     ls = ls * al + ps;
; #pragma unroll
;     for (int c = 0; c < 4; ++c) o[c] = o[c] * al;
	v_max_f32_e32 v223, v218, v138
	v_sub_f32_e32 v219, v218, v223
	v_sub_f32_e32 v220, v138, v223
	v_exp_f32_e32 v219, v219
	v_exp_f32_e32 v220, v220
	v_mov_b32_e32 v218, v223
	v_mul_f32_e32 v169, v169, v219
	v_fmac_f32_e32 v169, v139, v220
	v_mul_f32_e32 v0, v0, v219
	v_mul_f32_e32 v1, v1, v219
	v_mul_f32_e32 v2, v2, v219
	v_mul_f32_e32 v3, v3, v219
	v_mul_f32_e32 v4, v4, v219
	v_mul_f32_e32 v5, v5, v219
	v_mul_f32_e32 v6, v6, v219
	v_mul_f32_e32 v7, v7, v219
	v_mul_f32_e32 v8, v8, v219
	v_mul_f32_e32 v9, v9, v219
	v_mul_f32_e32 v10, v10, v219
	v_mul_f32_e32 v11, v11, v219
	v_mul_f32_e32 v12, v12, v219
	v_mul_f32_e32 v13, v13, v219
	v_mul_f32_e32 v14, v14, v219
	v_mul_f32_e32 v15, v15, v219
	v_mul_f32_e32 v16, v16, v219
	v_mul_f32_e32 v17, v17, v219
	v_mul_f32_e32 v18, v18, v219
	v_mul_f32_e32 v19, v19, v219
	v_mul_f32_e32 v20, v20, v219
	v_mul_f32_e32 v21, v21, v219
	v_mul_f32_e32 v22, v22, v219
	v_mul_f32_e32 v23, v23, v219
	v_mul_f32_e32 v24, v24, v219
	v_mul_f32_e32 v25, v25, v219
	v_mul_f32_e32 v26, v26, v219
	v_mul_f32_e32 v27, v27, v219
	v_mul_f32_e32 v28, v28, v219
	v_mul_f32_e32 v29, v29, v219
	v_mul_f32_e32 v30, v30, v219
	v_mul_f32_e32 v31, v31, v219
	v_mul_f32_e32 v32, v32, v219
	v_mul_f32_e32 v33, v33, v219
	v_mul_f32_e32 v34, v34, v219
	v_mul_f32_e32 v35, v35, v219
	v_mul_f32_e32 v36, v36, v219
	v_mul_f32_e32 v37, v37, v219
	v_mul_f32_e32 v38, v38, v219
	v_mul_f32_e32 v39, v39, v219
	v_mul_f32_e32 v40, v40, v219
	v_mul_f32_e32 v41, v41, v219
	v_mul_f32_e32 v42, v42, v219
	v_mul_f32_e32 v43, v43, v219
	v_mul_f32_e32 v44, v44, v219
	v_mul_f32_e32 v45, v45, v219
	v_mul_f32_e32 v46, v46, v219
	v_mul_f32_e32 v47, v47, v219
	v_mul_f32_e32 v48, v48, v219
	v_mul_f32_e32 v49, v49, v219
	v_mul_f32_e32 v50, v50, v219
	v_mul_f32_e32 v51, v51, v219
	v_mul_f32_e32 v52, v52, v219
	v_mul_f32_e32 v53, v53, v219
	v_mul_f32_e32 v54, v54, v219
	v_mul_f32_e32 v55, v55, v219
	v_mul_f32_e32 v56, v56, v219
	v_mul_f32_e32 v57, v57, v219
	v_mul_f32_e32 v58, v58, v219
	v_mul_f32_e32 v59, v59, v219
	v_mul_f32_e32 v60, v60, v219
	v_mul_f32_e32 v61, v61, v219
	v_mul_f32_e32 v62, v62, v219
	v_mul_f32_e32 v63, v63, v219
	v_fmac_f32_e32 v0, v72, v220
	v_fmac_f32_e32 v1, v73, v220
	v_fmac_f32_e32 v2, v74, v220
	v_fmac_f32_e32 v3, v75, v220
	v_fmac_f32_e32 v4, v76, v220
	v_fmac_f32_e32 v5, v77, v220
	v_fmac_f32_e32 v6, v78, v220
	v_fmac_f32_e32 v7, v79, v220
	v_fmac_f32_e32 v8, v80, v220
	v_fmac_f32_e32 v9, v81, v220
	v_fmac_f32_e32 v10, v82, v220
	v_fmac_f32_e32 v11, v83, v220
	v_fmac_f32_e32 v12, v84, v220
	v_fmac_f32_e32 v13, v85, v220
	v_fmac_f32_e32 v14, v86, v220
	v_fmac_f32_e32 v15, v87, v220
	v_fmac_f32_e32 v16, v88, v220
	v_fmac_f32_e32 v17, v89, v220
	v_fmac_f32_e32 v18, v90, v220
	v_fmac_f32_e32 v19, v91, v220
	v_fmac_f32_e32 v20, v92, v220
	v_fmac_f32_e32 v21, v93, v220
	v_fmac_f32_e32 v22, v94, v220
	v_fmac_f32_e32 v23, v95, v220
	v_fmac_f32_e32 v24, v96, v220
	v_fmac_f32_e32 v25, v97, v220
	v_fmac_f32_e32 v26, v98, v220
	v_fmac_f32_e32 v27, v99, v220
	v_fmac_f32_e32 v28, v100, v220
	v_fmac_f32_e32 v29, v101, v220
	v_fmac_f32_e32 v30, v102, v220
	v_fmac_f32_e32 v31, v103, v220
	v_fmac_f32_e32 v32, v104, v220
	v_fmac_f32_e32 v33, v105, v220
	v_fmac_f32_e32 v34, v108, v220
	v_fmac_f32_e32 v35, v109, v220
	v_fmac_f32_e32 v36, v110, v220
	v_fmac_f32_e32 v37, v111, v220
	v_fmac_f32_e32 v38, v112, v220
	v_fmac_f32_e32 v39, v113, v220
	v_fmac_f32_e32 v40, v114, v220
	v_fmac_f32_e32 v41, v115, v220
	v_fmac_f32_e32 v42, v116, v220
	v_fmac_f32_e32 v43, v117, v220
	v_fmac_f32_e32 v44, v118, v220
	v_fmac_f32_e32 v45, v119, v220
	v_fmac_f32_e32 v46, v120, v220
	v_fmac_f32_e32 v47, v121, v220
	v_fmac_f32_e32 v48, v122, v220
	v_fmac_f32_e32 v49, v123, v220
	v_fmac_f32_e32 v50, v124, v220
	v_fmac_f32_e32 v51, v125, v220
	v_fmac_f32_e32 v52, v126, v220
	v_fmac_f32_e32 v53, v127, v220
	v_fmac_f32_e32 v54, v128, v220
	v_fmac_f32_e32 v55, v129, v220
	v_fmac_f32_e32 v56, v130, v220
	v_fmac_f32_e32 v57, v131, v220
	v_fmac_f32_e32 v58, v132, v220
	v_fmac_f32_e32 v59, v133, v220
	v_fmac_f32_e32 v60, v134, v220
	v_fmac_f32_e32 v61, v135, v220
	v_fmac_f32_e32 v62, v136, v220
	v_fmac_f32_e32 v63, v137, v220
	ds_read2st64_b32 v[72:73], v222 offset0:0 offset1:1
	ds_read2st64_b32 v[74:75], v222 offset0:2 offset1:3
	ds_read2st64_b32 v[76:77], v222 offset0:4 offset1:5
	ds_read2st64_b32 v[78:79], v222 offset0:6 offset1:7
	ds_read2st64_b32 v[80:81], v222 offset0:8 offset1:9
	ds_read2st64_b32 v[82:83], v222 offset0:10 offset1:11
	ds_read2st64_b32 v[84:85], v222 offset0:12 offset1:13
	ds_read2st64_b32 v[86:87], v222 offset0:14 offset1:15
	ds_read2st64_b32 v[88:89], v222 offset0:16 offset1:17
	ds_read2st64_b32 v[90:91], v222 offset0:18 offset1:19
	ds_read2st64_b32 v[92:93], v222 offset0:20 offset1:21
	ds_read2st64_b32 v[94:95], v222 offset0:22 offset1:23
	ds_read2st64_b32 v[96:97], v222 offset0:24 offset1:25
	ds_read2st64_b32 v[98:99], v222 offset0:26 offset1:27
	ds_read2st64_b32 v[100:101], v222 offset0:28 offset1:29
	ds_read2st64_b32 v[102:103], v222 offset0:30 offset1:31
	ds_read2st64_b32 v[104:105], v222 offset0:32 offset1:33
	ds_read2st64_b32 v[108:109], v222 offset0:34 offset1:35
	ds_read2st64_b32 v[110:111], v222 offset0:36 offset1:37
	ds_read2st64_b32 v[112:113], v222 offset0:38 offset1:39
	ds_read2st64_b32 v[114:115], v222 offset0:40 offset1:41
	ds_read2st64_b32 v[116:117], v222 offset0:42 offset1:43
	ds_read2st64_b32 v[118:119], v222 offset0:44 offset1:45
	ds_read2st64_b32 v[120:121], v222 offset0:46 offset1:47
	ds_read2st64_b32 v[122:123], v222 offset0:48 offset1:49
	ds_read2st64_b32 v[124:125], v222 offset0:50 offset1:51
	ds_read2st64_b32 v[126:127], v222 offset0:52 offset1:53
	ds_read2st64_b32 v[128:129], v222 offset0:54 offset1:55
	ds_read2st64_b32 v[130:131], v222 offset0:56 offset1:57
	ds_read2st64_b32 v[132:133], v222 offset0:58 offset1:59
	ds_read2st64_b32 v[134:135], v222 offset0:60 offset1:61
	ds_read2st64_b32 v[136:137], v222 offset0:62 offset1:63
	ds_read2st64_b32 v[138:139], v222 offset0:64 offset1:65
	s_waitcnt lgkmcnt(0)
; template <class Prov, bool MASK>
; __device__ __forceinline__ void df_tile(const Prov& P, int comp, const bf16x8 (&qf)[4], int kv0, int kvlim, int lane, float& mx, float& ls, f32x16 (&o)[4]) {
;     ...
;     const float mn = fmaxf(mx, m), al = __builtin_amdgcn_exp2f(mx - mn);
;     mx = mn;
;     float ps = 0.f;
; #pragma unroll
;     for (int b2 = 0; b2 < 2; ++b2)
; #pragma unroll
;         for (int r = 0; r < 16; ++r) { const float p = __builtin_amdgcn_exp2f(s[b2][r] - mn); s[b2][r] = p; ps += p; }
;     ls = ls * al + ps;
; #pragma unroll
;     for (int c = 0; c < 4; ++c) o[c] = o[c] * al;
	v_max_f32_e32 v223, v218, v138
	v_sub_f32_e32 v219, v218, v223
	v_sub_f32_e32 v220, v138, v223
	v_exp_f32_e32 v219, v219
	v_exp_f32_e32 v220, v220
	v_mov_b32_e32 v218, v223
	v_mul_f32_e32 v169, v169, v219
	v_fmac_f32_e32 v169, v139, v220
	v_mul_f32_e32 v0, v0, v219
	v_mul_f32_e32 v1, v1, v219
	v_mul_f32_e32 v2, v2, v219
	v_mul_f32_e32 v3, v3, v219
	v_mul_f32_e32 v4, v4, v219
	v_mul_f32_e32 v5, v5, v219
	v_mul_f32_e32 v6, v6, v219
	v_mul_f32_e32 v7, v7, v219
	v_mul_f32_e32 v8, v8, v219
	v_mul_f32_e32 v9, v9, v219
	v_mul_f32_e32 v10, v10, v219
	v_mul_f32_e32 v11, v11, v219
	v_mul_f32_e32 v12, v12, v219
	v_mul_f32_e32 v13, v13, v219
	v_mul_f32_e32 v14, v14, v219
	v_mul_f32_e32 v15, v15, v219
	v_mul_f32_e32 v16, v16, v219
	v_mul_f32_e32 v17, v17, v219
	v_mul_f32_e32 v18, v18, v219
	v_mul_f32_e32 v19, v19, v219
	v_mul_f32_e32 v20, v20, v219
	v_mul_f32_e32 v21, v21, v219
	v_mul_f32_e32 v22, v22, v219
	v_mul_f32_e32 v23, v23, v219
	v_mul_f32_e32 v24, v24, v219
	v_mul_f32_e32 v25, v25, v219
	v_mul_f32_e32 v26, v26, v219
	v_mul_f32_e32 v27, v27, v219
	v_mul_f32_e32 v28, v28, v219
	v_mul_f32_e32 v29, v29, v219
	v_mul_f32_e32 v30, v30, v219
	v_mul_f32_e32 v31, v31, v219
	v_mul_f32_e32 v32, v32, v219
	v_mul_f32_e32 v33, v33, v219
	v_mul_f32_e32 v34, v34, v219
	v_mul_f32_e32 v35, v35, v219
	v_mul_f32_e32 v36, v36, v219
	v_mul_f32_e32 v37, v37, v219
	v_mul_f32_e32 v38, v38, v219
	v_mul_f32_e32 v39, v39, v219
	v_mul_f32_e32 v40, v40, v219
	v_mul_f32_e32 v41, v41, v219
	v_mul_f32_e32 v42, v42, v219
	v_mul_f32_e32 v43, v43, v219
	v_mul_f32_e32 v44, v44, v219
	v_mul_f32_e32 v45, v45, v219
	v_mul_f32_e32 v46, v46, v219
	v_mul_f32_e32 v47, v47, v219
	v_mul_f32_e32 v48, v48, v219
	v_mul_f32_e32 v49, v49, v219
	v_mul_f32_e32 v50, v50, v219
	v_mul_f32_e32 v51, v51, v219
	v_mul_f32_e32 v52, v52, v219
	v_mul_f32_e32 v53, v53, v219
	v_mul_f32_e32 v54, v54, v219
	v_mul_f32_e32 v55, v55, v219
	v_mul_f32_e32 v56, v56, v219
	v_mul_f32_e32 v57, v57, v219
	v_mul_f32_e32 v58, v58, v219
	v_mul_f32_e32 v59, v59, v219
	v_mul_f32_e32 v60, v60, v219
	v_mul_f32_e32 v61, v61, v219
	v_mul_f32_e32 v62, v62, v219
	v_mul_f32_e32 v63, v63, v219
	v_fmac_f32_e32 v0, v72, v220
	v_fmac_f32_e32 v1, v73, v220
	v_fmac_f32_e32 v2, v74, v220
	v_fmac_f32_e32 v3, v75, v220
	v_fmac_f32_e32 v4, v76, v220
	v_fmac_f32_e32 v5, v77, v220
	v_fmac_f32_e32 v6, v78, v220
	v_fmac_f32_e32 v7, v79, v220
	v_fmac_f32_e32 v8, v80, v220
	v_fmac_f32_e32 v9, v81, v220
	v_fmac_f32_e32 v10, v82, v220
	v_fmac_f32_e32 v11, v83, v220
	v_fmac_f32_e32 v12, v84, v220
	v_fmac_f32_e32 v13, v85, v220
	v_fmac_f32_e32 v14, v86, v220
	v_fmac_f32_e32 v15, v87, v220
	v_fmac_f32_e32 v16, v88, v220
	v_fmac_f32_e32 v17, v89, v220
	v_fmac_f32_e32 v18, v90, v220
	v_fmac_f32_e32 v19, v91, v220
	v_fmac_f32_e32 v20, v92, v220
	v_fmac_f32_e32 v21, v93, v220
	v_fmac_f32_e32 v22, v94, v220
	v_fmac_f32_e32 v23, v95, v220
	v_fmac_f32_e32 v24, v96, v220
	v_fmac_f32_e32 v25, v97, v220
	v_fmac_f32_e32 v26, v98, v220
	v_fmac_f32_e32 v27, v99, v220
	v_fmac_f32_e32 v28, v100, v220
	v_fmac_f32_e32 v29, v101, v220
	v_fmac_f32_e32 v30, v102, v220
	v_fmac_f32_e32 v31, v103, v220
	v_fmac_f32_e32 v32, v104, v220
	v_fmac_f32_e32 v33, v105, v220
	v_fmac_f32_e32 v34, v108, v220
	v_fmac_f32_e32 v35, v109, v220
	v_fmac_f32_e32 v36, v110, v220
	v_fmac_f32_e32 v37, v111, v220
	v_fmac_f32_e32 v38, v112, v220
	v_fmac_f32_e32 v39, v113, v220
	v_fmac_f32_e32 v40, v114, v220
	v_fmac_f32_e32 v41, v115, v220
	v_fmac_f32_e32 v42, v116, v220
	v_fmac_f32_e32 v43, v117, v220
	v_fmac_f32_e32 v44, v118, v220
	v_fmac_f32_e32 v45, v119, v220
	v_fmac_f32_e32 v46, v120, v220
	v_fmac_f32_e32 v47, v121, v220
	v_fmac_f32_e32 v48, v122, v220
	v_fmac_f32_e32 v49, v123, v220
	v_fmac_f32_e32 v50, v124, v220
	v_fmac_f32_e32 v51, v125, v220
	v_fmac_f32_e32 v52, v126, v220
	v_fmac_f32_e32 v53, v127, v220
	v_fmac_f32_e32 v54, v128, v220
	v_fmac_f32_e32 v55, v129, v220
	v_fmac_f32_e32 v56, v130, v220
	v_fmac_f32_e32 v57, v131, v220
	v_fmac_f32_e32 v58, v132, v220
	v_fmac_f32_e32 v59, v133, v220
	v_fmac_f32_e32 v60, v134, v220
	v_fmac_f32_e32 v61, v135, v220
	v_fmac_f32_e32 v62, v136, v220
	v_fmac_f32_e32 v63, v137, v220
	s_barrier

; __global__ void __launch_bounds__(NTHR) mega_fwd(Params Parg) {
;     extern __shared__ __attribute__((aligned(16))) unsigned char lds_raw[];
	.amdhsa_kernel _Z8mega_fwd6Params
		.amdhsa_group_segment_fixed_size 256
		.amdhsa_private_segment_fixed_size 0
		.amdhsa_kernarg_size 440
		.amdhsa_user_sgpr_count 2
		.amdhsa_user_sgpr_dispatch_ptr 0
		.amdhsa_user_sgpr_queue_ptr 0
		.amdhsa_user_sgpr_kernarg_segment_ptr 1
		.amdhsa_user_sgpr_dispatch_id 0
		.amdhsa_user_sgpr_kernarg_preload_length 0
		.amdhsa_user_sgpr_kernarg_preload_offset 0
		.amdhsa_user_sgpr_private_segment_size 0
		.amdhsa_uses_dynamic_stack 0
		.amdhsa_enable_private_segment 0
		.amdhsa_system_sgpr_workgroup_id_x 1
		.amdhsa_system_sgpr_workgroup_id_y 0
		.amdhsa_system_sgpr_workgroup_id_z 0
		.amdhsa_system_sgpr_workgroup_info 0
		.amdhsa_system_vgpr_workitem_id 2
		.amdhsa_next_free_vgpr 254
		.amdhsa_next_free_sgpr 102
		.amdhsa_accum_offset 256
		.amdhsa_reserve_vcc 1
		.amdhsa_float_round_mode_32 0
		.amdhsa_float_round_mode_16_64 0
		.amdhsa_float_denorm_mode_32 3
		.amdhsa_float_denorm_mode_16_64 3
		.amdhsa_dx10_clamp 1
		.amdhsa_ieee_mode 1
		.amdhsa_fp16_overflow 0
		.amdhsa_tg_split 0
		.amdhsa_exception_fp_ieee_invalid_op 0
		.amdhsa_exception_fp_denorm_src 0
		.amdhsa_exception_fp_ieee_div_zero 0
		.amdhsa_exception_fp_ieee_overflow 0
		.amdhsa_exception_fp_ieee_underflow 0
		.amdhsa_exception_fp_ieee_inexact 0
		.amdhsa_exception_int_div_zero 0
	.end_amdhsa_kernel

; __global__ void __launch_bounds__(NTHR) mega_fwd(Params Parg) {
;     extern __shared__ __attribute__((aligned(16))) unsigned char lds_raw[];
amdhsa.kernels:
  - .agpr_count:     0
    .args:
      - .offset:         0
        .size:           184
        .value_kind:     by_value
      - .offset:         184
        .size:           4
        .value_kind:     hidden_block_count_x
      - .offset:         188
        .size:           4
        .value_kind:     hidden_block_count_y
      - .offset:         192
        .size:           4
        .value_kind:     hidden_block_count_z
      - .offset:         196
        .size:           2
        .value_kind:     hidden_group_size_x
      - .offset:         198
        .size:           2
        .value_kind:     hidden_group_size_y
      - .offset:         200
        .size:           2
        .value_kind:     hidden_group_size_z
      - .offset:         202
        .size:           2
        .value_kind:     hidden_remainder_x
      - .offset:         204
        .size:           2
        .value_kind:     hidden_remainder_y
      - .offset:         206
        .size:           2
        .value_kind:     hidden_remainder_z
      - .offset:         224
        .size:           8
        .value_kind:     hidden_global_offset_x
      - .offset:         232
        .size:           8
        .value_kind:     hidden_global_offset_y
      - .offset:         240
        .size:           8
        .value_kind:     hidden_global_offset_z
      - .offset:         248
        .size:           2
        .value_kind:     hidden_grid_dims
      - .offset:         272
        .size:           8
        .value_kind:     hidden_multigrid_sync_arg
      - .offset:         304
        .size:           4
        .value_kind:     hidden_dynamic_lds_size
    .group_segment_fixed_size: 256
    .kernarg_segment_align: 8
    .kernarg_segment_size: 440
    .language:       OpenCL C
    .language_version:
      - 2
      - 0
    .max_flat_workgroup_size: 512
    .name:           _Z8mega_fwd6Params
    .private_segment_fixed_size: 0
    .sgpr_count:     108
    .sgpr_spill_count: 88
    .symbol:         _Z8mega_fwd6Params.kd
    .uniform_work_group_size: 1
    .uses_dynamic_stack: false
    .vgpr_count:     254
    .vgpr_spill_count: 0
    .wavefront_size: 64
